# speedup vs baseline: 1.0045x; 1.0022x over previous
; DEVINL float shup(float v, int off, int lane) { return __int_as_float(__builtin_amdgcn_ds_bpermute(((lane - off) & 63) << 2, __float_as_int(v))); }
; DEVINL void ssd1_item(const Params& p, int layer, int item, char* smem, int wv) {
;     ...
;     int hh = wid, hd = g * 8 + hh;
;     float a = -expf(p.a_log[layer * 16 + hd]);
;     float v0 = dtf[(size_t)(tok0 + 2 * lane) * 16 + hd] * a;
;     float v1 = dtf[(size_t)(tok0 + 2 * lane + 1) * 16 + hd] * a;
;     float s = v0 + v1;
; #pragma unroll
;     for (int off = 1; off < 64; off <<= 1) { float tt = shup(s, off, lane); if (lane >= off) s += tt; }
;     float ex = s - (v0 + v1);
;     ac[hh * 128 + 2 * lane] = ex + v0; ac[hh * 128 + 2 * lane + 1] = ex + v0 + v1;
; DEVINL void phase_mix(const Params& p, int layer, char* smem, int wv, int rep) {
;     ...
;       int it = next_item(ctr, smem, wv);
;       if (it >= 256) break;
.LBB0_591:
	s_or_b64 exec, exec, s[0:1]
	s_waitcnt lgkmcnt(0)
	s_barrier
	ds_read_b32 v0, v124
	s_movk_i32 s0, 0xff
	s_waitcnt lgkmcnt(0)
	v_cmp_lt_i32_e32 vcc, s0, v0
	v_readfirstlane_b32 s2, v0
	s_mov_b64 s[0:1], -1
	s_cbranch_vccnz .LBB0_586
	v_mov_b32_e32 v22, v176
	s_and_b32 s28, s2, 1
	v_readfirstlane_b32 s0, v22
	s_bfe_u32 s24, s2, 0x50001
	s_ashr_i32 s25, s2, 6
	s_ashr_i32 s26, s0, 6
	s_lshl_b32 s0, s25, 12
	s_lshl_b32 s1, s24, 7
	s_lshl_b32 s76, s28, 3
	s_or_b32 s27, s1, s0
	s_add_i32 s0, s26, s76
	s_ashr_i32 s1, s0, 31
	v_readlane_b32 s4, v254, 2
	s_lshl_b64 s[2:3], s[0:1], 2
	v_readlane_b32 s16, v254, 14
	v_readlane_b32 s17, v254, 15
	s_add_u32 s2, s16, s2
	s_addc_u32 s3, s17, s3
	global_load_dword v0, v1, s[2:3]
	v_and_b32_e32 v127, 63, v22
	v_lshlrev_b32_e32 v23, 1, v127
	v_or_b32_e32 v2, s27, v23
	v_ashrrev_i32_e32 v3, 31, v2
	v_lshl_add_u64 v[4:5], v[2:3], 4, s[0:1]
	v_or_b32_e32 v2, 1, v2
	v_ashrrev_i32_e32 v3, 31, v2
	v_readlane_b32 s2, v254, 52
	v_lshl_add_u64 v[2:3], v[2:3], 4, s[0:1]
	v_readlane_b32 s3, v254, 53
	v_lshlrev_b64 v[2:3], 2, v[2:3]
	v_lshlrev_b64 v[4:5], 2, v[4:5]
	v_lshl_add_u64 v[8:9], s[2:3], 0, v[2:3]
	v_lshl_add_u64 v[6:7], s[2:3], 0, v[4:5]
	global_load_dword v8, v[8:9], off
	s_nop 0
	global_load_dword v9, v[6:7], off
	s_mov_b32 s0, 0x3fb8aa3b
	s_mov_b32 s1, 0xc2ce8ed0
	s_mov_b32 s2, 0x42b17218
	v_mov_b64_e32 v[18:19], s[90:91]
	v_or_b32_e32 v40, s27, v127
	s_lshl_b32 s16, s26, 4
	s_lshl_b32 s74, s28, 8
	s_ashr_i32 s17, s16, 31
	v_or_b32_e32 v57, 64, v127
	v_and_b32_e32 v56, 15, v22
	v_add_u32_e32 v48, 0, v23
	v_bfe_u32 v47, v22, 4, 2
	v_lshlrev_b32_e32 v44, 3, v47
	v_or_b32_e32 v41, s27, v56
	s_waitcnt vmcnt(10)
	v_lshlrev_b32_e32 v64, 1, v44
	v_readlane_b32 s5, v254, 3
	v_readlane_b32 s6, v254, 4
	v_readlane_b32 s7, v254, 5
	v_readlane_b32 s8, v254, 6
	v_readlane_b32 s9, v254, 7
	v_readlane_b32 s10, v254, 8
	v_readlane_b32 s11, v254, 9
	v_readlane_b32 s12, v254, 10
	v_readlane_b32 s13, v254, 11
	v_readlane_b32 s14, v254, 12
	v_readlane_b32 s15, v254, 13
	v_readlane_b32 s18, v254, 16
	v_readlane_b32 s19, v254, 17
	s_waitcnt vmcnt(2)
	v_mul_f32_e32 v6, 0x3fb8aa3b, v0
	v_fma_f32 v7, v0, s0, -v6
	v_rndne_f32_e32 v10, v6
	v_fmac_f32_e32 v7, 0x32a5705f, v0
	v_sub_f32_e32 v6, v6, v10
	v_add_f32_e32 v6, v6, v7
	v_cvt_i32_f32_e32 v10, v10
	v_exp_f32_e32 v6, v6
	v_cmp_ngt_f32_e32 vcc, s1, v0
	v_lshlrev_b32_e32 v7, 2, v22
	v_add_u32_e32 v11, 0xfc, v7
	v_ldexp_f32 v6, v6, v10
	v_cndmask_b32_e32 v6, 0, v6, vcc
	v_cmp_nlt_f32_e32 vcc, s2, v0
	v_and_b32_e32 v11, 0xfc, v11
	v_add_u32_e32 v10, 0xf8, v7
	v_cndmask_b32_e32 v0, v125, v6, vcc
	s_waitcnt vmcnt(1)
	v_mul_f32_e32 v6, v8, v0
	s_waitcnt vmcnt(0)
	v_fma_f32 v12, v9, -v0, -v6
	ds_bpermute_b32 v6, v11, v12
	v_cmp_eq_u32_e32 vcc, 0, v127
	v_and_b32_e32 v10, 0xfc, v10
	v_add_u32_e32 v11, 0xf0, v7
	v_and_b32_e32 v11, 0xfc, v11
	s_waitcnt lgkmcnt(0)
	v_add_f32_e32 v6, v12, v6
	v_cndmask_b32_e32 v6, v6, v12, vcc
	ds_bpermute_b32 v10, v10, v6
	v_cmp_gt_u32_e32 vcc, 2, v127
	s_movk_i32 s0, 0x80
	v_add_u32_e32 v13, 0xc0, v7
	v_bitop3_b32 v14, v7, s0, v126 bitop3:0x6c
	s_waitcnt lgkmcnt(0)
	v_add_f32_e32 v10, v6, v10
	v_cndmask_b32_e32 v6, v10, v6, vcc
	ds_bpermute_b32 v10, v11, v6
	v_add_u32_e32 v11, 0xe0, v7
	v_cmp_gt_u32_e32 vcc, 4, v127
	v_and_b32_e32 v7, 0xfc, v11
	v_and_b32_e32 v13, 0xfc, v13
	s_waitcnt lgkmcnt(0)
	v_add_f32_e32 v10, v6, v10
	v_cndmask_b32_e32 v10, v10, v6, vcc
	ds_bpermute_b32 v11, v7, v10
	v_cmp_gt_u32_e32 vcc, 8, v127
	v_mad_i64_i32 v[6:7], s[0:1], v40, s29, v[18:19]
	v_readlane_b32 s0, v254, 56
	s_waitcnt lgkmcnt(0)
	v_add_f32_e32 v11, v10, v11
	v_cndmask_b32_e32 v10, v11, v10, vcc
	ds_bpermute_b32 v11, v13, v10
	v_cmp_gt_u32_e32 vcc, 16, v127
	v_readlane_b32 s1, v254, 57
	v_lshl_add_u64 v[6:7], v[6:7], 0, s[74:75]
	s_waitcnt lgkmcnt(0)
	v_add_f32_e32 v11, v10, v11
	v_cndmask_b32_e32 v13, v11, v10, vcc
	ds_bpermute_b32 v14, v14, v13
	v_lshl_add_u64 v[4:5], s[0:1], 0, v[4:5]
	v_lshl_add_u64 v[2:3], s[0:1], 0, v[2:3]
	s_lshl_b64 s[0:1], s[16:17], 1
	v_lshl_add_u64 v[10:11], v[6:7], 0, s[0:1]
	s_waitcnt lgkmcnt(0)
; DEVINL f32x4 mfma16(bf16x8 a, bf16x8 b, f32x4 c) { return __builtin_amdgcn_mfma_f32_16x16x32_bf16(a, b, c, 0, 0, 0); }
; DEVINL float shup(float v, int off, int lane) { return __int_as_float(__builtin_amdgcn_ds_bpermute(((lane - off) & 63) << 2, __float_as_int(v))); }
; DEVINL void ssd1_item(const Params& p, int layer, int item, char* smem, int wv) {
;     ...
;     for (int off = 1; off < 64; off <<= 1) { float tt = shup(s, off, lane); if (lane >= off) s += tt; }
;     float ex = s - (v0 + v1);
;     ac[hh * 128 + 2 * lane] = ex + v0; ac[hh * 128 + 2 * lane + 1] = ex + v0 + v1;
;     acumg[(size_t)(tok0 + 2 * lane) * 16 + hd] = ex + v0;
;     acumg[(size_t)(tok0 + 2 * lane + 1) * 16 + hd] = ex + v0 + v1;
;   }
; #pragma unroll
;   for (int i = 0; i < 4; ++i) {
;     const int combo = wid * 4 + i; const int nc = combo >> 1, s = lane + 64 * (combo & 1);
;     bf16x8 raw = *(const bf16x8*)(xc + (size_t)(tok0 + s) * 1536 + 1024 + g * 128 + nc * 8);
; #pragma unroll
;     for (int k = 0; k < 8; ++k) Bt[(nc * 8 + k) * 136 + s] = (u16)raw[k];
;   }
;   f32x4 G[8];
; #pragma unroll
;   for (int st = 0; st < 8; ++st) G[st] = f32x4{0.f, 0.f, 0.f, 0.f};
; #pragma unroll
;   for (int kc = 0; kc < 4; ++kc) {
;     bf16x8 cf = *(const bf16x8*)(xc + (size_t)(tok0 + LT * 16 + fr) * 1536 + 1280 + g * 128 + kc * 32 + fq * 8);
; #pragma unroll
;     for (int st = 0; st < 8; ++st) {
;       if (st <= LT) {
;         bf16x8 bfm = *(const bf16x8*)(xc + (size_t)(tok0 + st * 16 + fr) * 1536 + 1024 + g * 128 + kc * 32 + fq * 8);
;         G[st] = mfma16(bfm, cf, G[st]);
;       }
;     }
;   }
	v_add_f32_e32 v6, v13, v14
	v_cmp_gt_u32_e32 vcc, 32, v127
	s_lshl_b32 s17, s28, 7
	s_nop 0
	v_cndmask_b32_e32 v6, v6, v13, vcc
	v_sub_f32_e32 v6, v6, v12
	v_fma_f32 v20, v9, -v0, v6
	v_fma_f32 v21, v8, -v0, v20
	v_or_b32_e32 v0, s27, v57
	v_mad_i64_i32 v[6:7], s[2:3], v0, s29, v[18:19]
	v_lshl_add_u64 v[6:7], v[6:7], 0, s[74:75]
	v_lshl_add_u64 v[14:15], v[6:7], 0, s[0:1]
	s_add_i32 s0, s16, s27
	v_or_b32_e32 v24, s0, v56
	v_mad_i64_i32 v[18:19], s[0:1], v24, s29, v[18:19]
	v_and_b32_e32 v0, 48, v22
	v_lshl_add_u64 v[18:19], v[18:19], 0, s[74:75]
	global_store_dword v[4:5], v20, off
	global_store_dword v[2:3], v21, off
	v_lshl_add_u64 v[42:43], v[18:19], 0, v[0:1]
	s_lshl_b32 s98, s17, 1
	s_mov_b32 s99, 0
	v_mov_b32_e32 v232, v64
	v_mov_b32_e32 v233, 0
	v_mov_b32_e32 v234, v41
	v_mov_b64_e32 v[216:217], s[90:91]
	v_mad_i64_i32 v[216:217], s[100:101], v234, s29, v[216:217]
	v_lshl_add_u64 v[216:217], v[216:217], 0, s[98:99]
	v_lshl_add_u64 v[216:217], v[216:217], 0, v[232:233]
	v_or_b32_e32 v234, 16, v41
	v_mov_b64_e32 v[218:219], s[90:91]
	v_mad_i64_i32 v[218:219], s[100:101], v234, s29, v[218:219]
	v_lshl_add_u64 v[218:219], v[218:219], 0, s[98:99]
	v_lshl_add_u64 v[218:219], v[218:219], 0, v[232:233]
	v_or_b32_e32 v234, 32, v41
	v_mov_b64_e32 v[220:221], s[90:91]
	v_mad_i64_i32 v[220:221], s[100:101], v234, s29, v[220:221]
	v_lshl_add_u64 v[220:221], v[220:221], 0, s[98:99]
	v_lshl_add_u64 v[220:221], v[220:221], 0, v[232:233]
	v_or_b32_e32 v234, 48, v41
	v_mov_b64_e32 v[222:223], s[90:91]
	v_mad_i64_i32 v[222:223], s[100:101], v234, s29, v[222:223]
	v_lshl_add_u64 v[222:223], v[222:223], 0, s[98:99]
	v_lshl_add_u64 v[222:223], v[222:223], 0, v[232:233]
	v_or_b32_e32 v234, 64, v41
	v_mov_b64_e32 v[224:225], s[90:91]
	v_mad_i64_i32 v[224:225], s[100:101], v234, s29, v[224:225]
	v_lshl_add_u64 v[224:225], v[224:225], 0, s[98:99]
	v_lshl_add_u64 v[224:225], v[224:225], 0, v[232:233]
	v_or_b32_e32 v234, 80, v41
	v_mov_b64_e32 v[226:227], s[90:91]
	v_mad_i64_i32 v[226:227], s[100:101], v234, s29, v[226:227]
	v_lshl_add_u64 v[226:227], v[226:227], 0, s[98:99]
	v_lshl_add_u64 v[226:227], v[226:227], 0, v[232:233]
	v_or_b32_e32 v234, 96, v41
	v_mov_b64_e32 v[228:229], s[90:91]
	v_mad_i64_i32 v[228:229], s[100:101], v234, s29, v[228:229]
	v_lshl_add_u64 v[228:229], v[228:229], 0, s[98:99]
	v_lshl_add_u64 v[228:229], v[228:229], 0, v[232:233]
	v_or_b32_e32 v234, 112, v41
	v_mov_b64_e32 v[230:231], s[90:91]
	v_mad_i64_i32 v[230:231], s[100:101], v234, s29, v[230:231]
	v_lshl_add_u64 v[230:231], v[230:231], 0, s[98:99]
	v_lshl_add_u64 v[230:231], v[230:231], 0, v[232:233]
	global_load_dwordx4 v[2:5], v[10:11], off offset:2048
	global_load_dwordx4 v[6:9], v[14:15], off offset:2048
	s_nop 0
	global_load_dwordx4 v[10:13], v[10:11], off offset:2064
	s_nop 0
	global_load_dwordx4 v[14:17], v[14:15], off offset:2064
	s_mul_i32 s0, s26, 0x1100
	global_load_dwordx4 v[32:35], v[42:43], off offset:2560
	v_add_u32_e32 v0, s0, v48
	s_lshl_b32 s0, s26, 9
	s_add_i32 s0, s0, 0
	s_or_b32 s1, s16, 8
	v_lshl_add_u32 v18, v127, 3, s0
	s_cmp_gt_i32 s26, -1
	s_mulk_i32 s1, 0x110
	v_add_u32_e32 v18, 0x19800, v18
	s_cselect_b64 s[2:3], -1, 0
	s_cmp_lt_i32 s26, 0
	v_add_u32_e32 v19, s1, v48
	ds_write_b64 v18, v[20:21]
	s_waitcnt vmcnt(4)
	ds_write_b16 v0, v2
	ds_write_b16_d16_hi v0, v2 offset:272
	ds_write_b16 v0, v3 offset:544
	ds_write_b16_d16_hi v0, v3 offset:816
	ds_write_b16 v0, v4 offset:1088
	ds_write_b16_d16_hi v0, v4 offset:1360
	ds_write_b16 v0, v5 offset:1632
	ds_write_b16_d16_hi v0, v5 offset:1904
	s_waitcnt vmcnt(3)
	ds_write_b16 v0, v6 offset:128
	ds_write_b16_d16_hi v0, v6 offset:400
	ds_write_b16 v0, v7 offset:672
	ds_write_b16_d16_hi v0, v7 offset:944
	ds_write_b16 v0, v8 offset:1216
	ds_write_b16_d16_hi v0, v8 offset:1488
	ds_write_b16 v0, v9 offset:1760
	ds_write_b16_d16_hi v0, v9 offset:2032
	s_waitcnt vmcnt(2)
	ds_write_b16 v19, v10
	ds_write_b16_d16_hi v0, v10 offset:2448
	ds_write_b16 v0, v11 offset:2720
	ds_write_b16_d16_hi v0, v11 offset:2992
	ds_write_b16 v0, v12 offset:3264
	ds_write_b16_d16_hi v0, v12 offset:3536
	ds_write_b16 v0, v13 offset:3808
	ds_write_b16_d16_hi v0, v13 offset:4080
	s_waitcnt vmcnt(1)
	ds_write_b16 v19, v14 offset:128
	ds_write_b16_d16_hi v0, v14 offset:2576
	ds_write_b16 v0, v15 offset:2848
	ds_write_b16_d16_hi v0, v15 offset:3120
	ds_write_b16 v0, v16 offset:3392
	ds_write_b16_d16_hi v0, v16 offset:3664
	ds_write_b16 v0, v17 offset:3936
	ds_write_b16_d16_hi v0, v17 offset:4208
	global_load_dwordx4 v[184:187], v[216:217], off offset:2048
	global_load_dwordx4 v[188:191], v[218:219], off offset:2048
	global_load_dwordx4 v[192:195], v[220:221], off offset:2048
	global_load_dwordx4 v[196:199], v[222:223], off offset:2048
	global_load_dwordx4 v[200:203], v[224:225], off offset:2048
	global_load_dwordx4 v[204:207], v[226:227], off offset:2048
	global_load_dwordx4 v[208:211], v[228:229], off offset:2048
	global_load_dwordx4 v[212:215], v[230:231], off offset:2048
	s_cbranch_scc1 .LBB0_594
	v_mov_b64_e32 v[2:3], s[90:91]
	v_mad_i64_i32 v[2:3], s[0:1], v41, s29, v[2:3]
	s_lshl_b32 s74, s17, 1
	v_lshl_add_u64 v[2:3], v[2:3], 0, s[74:75]
	v_mov_b32_e32 v65, v1
	v_lshl_add_u64 v[2:3], v[2:3], 0, v[64:65]
	s_waitcnt vmcnt(0)
	v_mfma_f32_16x16x32_bf16 v[4:7], v[184:187], v[32:35], 0
	s_branch .LBB0_595

; DEVINL f32x4 mfma16(bf16x8 a, bf16x8 b, f32x4 c) { return __builtin_amdgcn_mfma_f32_16x16x32_bf16(a, b, c, 0, 0, 0); }
; DEVINL void ssd1_item(const Params& p, int layer, int item, char* smem, int wv) {
;     ...
;     for (int st = 0; st < 8; ++st) {
;       if (st <= LT) {
;         bf16x8 bfm = *(const bf16x8*)(xc + (size_t)(tok0 + st * 16 + fr) * 1536 + 1024 + g * 128 + kc * 32 + fq * 8);
;         G[st] = mfma16(bfm, cf, G[st]);
;       }
.LBB0_595:
	s_cmp_gt_i32 s26, 0
	s_cselect_b64 s[4:5], -1, 0
	s_cmp_lt_i32 s26, 1
	v_or_b32_e32 v45, 16, v41
	s_cbranch_scc1 .LBB0_597
	v_mov_b64_e32 v[2:3], s[90:91]
	v_mad_i64_i32 v[2:3], s[0:1], v45, s29, v[2:3]
	s_lshl_b32 s74, s17, 1
	v_lshl_add_u64 v[2:3], v[2:3], 0, s[74:75]
	v_mov_b32_e32 v65, v1
	v_lshl_add_u64 v[2:3], v[2:3], 0, v[64:65]
	s_waitcnt vmcnt(0)
	v_mfma_f32_16x16x32_bf16 v[8:11], v[188:191], v[32:35], 0
	s_branch .LBB0_598

; DEVINL f32x4 mfma16(bf16x8 a, bf16x8 b, f32x4 c) { return __builtin_amdgcn_mfma_f32_16x16x32_bf16(a, b, c, 0, 0, 0); }
; DEVINL void ssd1_item(const Params& p, int layer, int item, char* smem, int wv) {
;     ...
;     for (int st = 0; st < 8; ++st) {
;       if (st <= LT) {
;         bf16x8 bfm = *(const bf16x8*)(xc + (size_t)(tok0 + st * 16 + fr) * 1536 + 1024 + g * 128 + kc * 32 + fq * 8);
;         G[st] = mfma16(bfm, cf, G[st]);
;       }
.LBB0_598:
	s_cmp_gt_i32 s26, 1
	s_cselect_b64 s[6:7], -1, 0
	s_cmp_lt_i32 s26, 2
	v_or_b32_e32 v46, 32, v41
	s_cbranch_scc1 .LBB0_600
	v_mov_b64_e32 v[2:3], s[90:91]
	v_mad_i64_i32 v[2:3], s[0:1], v46, s29, v[2:3]
	s_lshl_b32 s74, s17, 1
	v_lshl_add_u64 v[2:3], v[2:3], 0, s[74:75]
	v_mov_b32_e32 v65, v1
	v_lshl_add_u64 v[2:3], v[2:3], 0, v[64:65]
	s_waitcnt vmcnt(0)
	v_mfma_f32_16x16x32_bf16 v[12:15], v[192:195], v[32:35], 0
	s_branch .LBB0_601

; DEVINL f32x4 mfma16(bf16x8 a, bf16x8 b, f32x4 c) { return __builtin_amdgcn_mfma_f32_16x16x32_bf16(a, b, c, 0, 0, 0); }
; DEVINL void ssd1_item(const Params& p, int layer, int item, char* smem, int wv) {
;     ...
;     for (int st = 0; st < 8; ++st) {
;       if (st <= LT) {
;         bf16x8 bfm = *(const bf16x8*)(xc + (size_t)(tok0 + st * 16 + fr) * 1536 + 1024 + g * 128 + kc * 32 + fq * 8);
;         G[st] = mfma16(bfm, cf, G[st]);
;       }
.LBB0_601:
	s_cmp_gt_i32 s26, 2
	s_cselect_b64 s[12:13], -1, 0
	s_cmp_lt_i32 s26, 3
	v_or_b32_e32 v49, 48, v41
	s_cbranch_scc1 .LBB0_603
	v_mov_b64_e32 v[2:3], s[90:91]
	v_mad_i64_i32 v[2:3], s[0:1], v49, s29, v[2:3]
	s_lshl_b32 s74, s17, 1
	v_lshl_add_u64 v[2:3], v[2:3], 0, s[74:75]
	v_mov_b32_e32 v65, v1
	v_lshl_add_u64 v[2:3], v[2:3], 0, v[64:65]
	s_waitcnt vmcnt(0)
	v_mfma_f32_16x16x32_bf16 v[16:19], v[196:199], v[32:35], 0
	s_branch .LBB0_604

; DEVINL f32x4 mfma16(bf16x8 a, bf16x8 b, f32x4 c) { return __builtin_amdgcn_mfma_f32_16x16x32_bf16(a, b, c, 0, 0, 0); }
; DEVINL void ssd1_item(const Params& p, int layer, int item, char* smem, int wv) {
;     ...
;     for (int st = 0; st < 8; ++st) {
;       if (st <= LT) {
;         bf16x8 bfm = *(const bf16x8*)(xc + (size_t)(tok0 + st * 16 + fr) * 1536 + 1024 + g * 128 + kc * 32 + fq * 8);
;         G[st] = mfma16(bfm, cf, G[st]);
;       }
.LBB0_604:
	s_cmp_gt_i32 s26, 3
	s_cselect_b64 s[14:15], -1, 0
	s_cmp_lt_i32 s26, 4
	v_or_b32_e32 v50, 64, v41
	s_cbranch_scc1 .LBB0_606
	v_mov_b64_e32 v[2:3], s[90:91]
	v_mad_i64_i32 v[2:3], s[0:1], v50, s29, v[2:3]
	s_lshl_b32 s74, s17, 1
	v_lshl_add_u64 v[2:3], v[2:3], 0, s[74:75]
	v_mov_b32_e32 v65, v1
	v_lshl_add_u64 v[2:3], v[2:3], 0, v[64:65]
	s_waitcnt vmcnt(0)
	v_mfma_f32_16x16x32_bf16 v[20:23], v[200:203], v[32:35], 0
	s_branch .LBB0_607

; DEVINL f32x4 mfma16(bf16x8 a, bf16x8 b, f32x4 c) { return __builtin_amdgcn_mfma_f32_16x16x32_bf16(a, b, c, 0, 0, 0); }
; DEVINL void ssd1_item(const Params& p, int layer, int item, char* smem, int wv) {
;     ...
;     for (int st = 0; st < 8; ++st) {
;       if (st <= LT) {
;         bf16x8 bfm = *(const bf16x8*)(xc + (size_t)(tok0 + st * 16 + fr) * 1536 + 1024 + g * 128 + kc * 32 + fq * 8);
;         G[st] = mfma16(bfm, cf, G[st]);
;       }
.LBB0_607:
	s_cmp_gt_i32 s26, 4
	s_cselect_b64 s[18:19], -1, 0
	s_cmp_lt_i32 s26, 5
	v_or_b32_e32 v51, 0x50, v41
	s_cbranch_scc1 .LBB0_609
	v_mov_b64_e32 v[2:3], s[90:91]
	v_mad_i64_i32 v[2:3], s[0:1], v51, s29, v[2:3]
	s_lshl_b32 s74, s17, 1
	v_lshl_add_u64 v[2:3], v[2:3], 0, s[74:75]
	v_mov_b32_e32 v65, v1
	v_lshl_add_u64 v[2:3], v[2:3], 0, v[64:65]
	s_waitcnt vmcnt(0)
	v_mfma_f32_16x16x32_bf16 v[24:27], v[204:207], v[32:35], 0
	s_branch .LBB0_610

; DEVINL f32x4 mfma16(bf16x8 a, bf16x8 b, f32x4 c) { return __builtin_amdgcn_mfma_f32_16x16x32_bf16(a, b, c, 0, 0, 0); }
; DEVINL void ssd1_item(const Params& p, int layer, int item, char* smem, int wv) {
;     ...
;     for (int st = 0; st < 8; ++st) {
;       if (st <= LT) {
;         bf16x8 bfm = *(const bf16x8*)(xc + (size_t)(tok0 + st * 16 + fr) * 1536 + 1024 + g * 128 + kc * 32 + fq * 8);
;         G[st] = mfma16(bfm, cf, G[st]);
;       }
.LBB0_610:
	s_cmp_gt_i32 s26, 5
	s_cselect_b64 s[20:21], -1, 0
	s_cmp_lt_i32 s26, 6
	v_or_b32_e32 v52, 0x60, v41
	s_cbranch_scc1 .LBB0_612
	v_mov_b64_e32 v[2:3], s[90:91]
	v_mad_i64_i32 v[2:3], s[0:1], v52, s29, v[2:3]
	s_lshl_b32 s74, s17, 1
	v_lshl_add_u64 v[2:3], v[2:3], 0, s[74:75]
	v_mov_b32_e32 v65, v1
	v_lshl_add_u64 v[2:3], v[2:3], 0, v[64:65]
	s_waitcnt vmcnt(0)
	v_mfma_f32_16x16x32_bf16 v[28:31], v[208:211], v[32:35], 0
	s_branch .LBB0_613

; DEVINL f32x4 mfma16(bf16x8 a, bf16x8 b, f32x4 c) { return __builtin_amdgcn_mfma_f32_16x16x32_bf16(a, b, c, 0, 0, 0); }
; DEVINL void ssd1_item(const Params& p, int layer, int item, char* smem, int wv) {
;     ...
;     for (int st = 0; st < 8; ++st) {
;       if (st <= LT) {
;         bf16x8 bfm = *(const bf16x8*)(xc + (size_t)(tok0 + st * 16 + fr) * 1536 + 1024 + g * 128 + kc * 32 + fq * 8);
;         G[st] = mfma16(bfm, cf, G[st]);
;       }
.LBB0_613:
	s_cmp_gt_i32 s26, 6
	s_cselect_b64 s[22:23], -1, 0
	s_cmp_lt_i32 s26, 7
	v_or_b32_e32 v53, 0x70, v41
	s_cbranch_scc1 .LBB0_615
	v_mov_b64_e32 v[2:3], s[90:91]
	v_mad_i64_i32 v[2:3], s[0:1], v53, s29, v[2:3]
	s_lshl_b32 s74, s17, 1
	v_lshl_add_u64 v[2:3], v[2:3], 0, s[74:75]
	v_mov_b32_e32 v65, v1
	v_lshl_add_u64 v[2:3], v[2:3], 0, v[64:65]
	s_waitcnt vmcnt(0)
	v_mfma_f32_16x16x32_bf16 v[32:35], v[212:215], v[32:35], 0
	s_branch .LBB0_616

; DEVINL f32x4 mfma16(bf16x8 a, bf16x8 b, f32x4 c) { return __builtin_amdgcn_mfma_f32_16x16x32_bf16(a, b, c, 0, 0, 0); }
; DEVINL void ssd1_item(const Params& p, int layer, int item, char* smem, int wv) {
;     ...
;   for (int kc = 0; kc < 4; ++kc) {
;     bf16x8 cf = *(const bf16x8*)(xc + (size_t)(tok0 + LT * 16 + fr) * 1536 + 1280 + g * 128 + kc * 32 + fq * 8);
; #pragma unroll
;     for (int st = 0; st < 8; ++st) {
;       if (st <= LT) {
;         bf16x8 bfm = *(const bf16x8*)(xc + (size_t)(tok0 + st * 16 + fr) * 1536 + 1024 + g * 128 + kc * 32 + fq * 8);
;         G[st] = mfma16(bfm, cf, G[st]);
;       }
.LBB0_616:
	global_load_dwordx4 v[36:39], v[42:43], off offset:2624
	global_load_dwordx4 v[184:187], v[216:217], off offset:2112
	global_load_dwordx4 v[188:191], v[218:219], off offset:2112
	global_load_dwordx4 v[192:195], v[220:221], off offset:2112
	global_load_dwordx4 v[196:199], v[222:223], off offset:2112
	global_load_dwordx4 v[200:203], v[224:225], off offset:2112
	global_load_dwordx4 v[204:207], v[226:227], off offset:2112
	global_load_dwordx4 v[208:211], v[228:229], off offset:2112
	global_load_dwordx4 v[212:215], v[230:231], off offset:2112
	v_cndmask_b32_e64 v0, 0, 1, s[2:3]
	v_cmp_ne_u32_e64 s[0:1], 1, v0
	s_andn2_b64 vcc, exec, s[2:3]
	s_cbranch_vccnz .LBB0_640
	v_mov_b64_e32 v[2:3], s[90:91]
	v_mad_i64_i32 v[2:3], s[2:3], v41, s29, v[2:3]
	s_lshl_b32 s74, s17, 1
	v_lshl_add_u64 v[2:3], v[2:3], 0, s[74:75]
	v_mov_b32_e32 v65, v1
	v_lshl_add_u64 v[2:3], v[2:3], 0, v[64:65]
	s_waitcnt vmcnt(0)
	v_mfma_f32_16x16x32_bf16 v[4:7], v[184:187], v[36:39], v[4:7]
	v_cndmask_b32_e64 v0, 0, 1, s[4:5]
	v_cmp_ne_u32_e64 s[8:9], 1, v0
	s_andn2_b64 vcc, exec, s[4:5]
	s_cbranch_vccz .LBB0_641

; DEVINL f32x4 mfma16(bf16x8 a, bf16x8 b, f32x4 c) { return __builtin_amdgcn_mfma_f32_16x16x32_bf16(a, b, c, 0, 0, 0); }
; DEVINL void ssd1_item(const Params& p, int layer, int item, char* smem, int wv) {
;     ...
;     for (int st = 0; st < 8; ++st) {
;       if (st <= LT) {
;         bf16x8 bfm = *(const bf16x8*)(xc + (size_t)(tok0 + st * 16 + fr) * 1536 + 1024 + g * 128 + kc * 32 + fq * 8);
;         G[st] = mfma16(bfm, cf, G[st]);
;       }
.LBB0_619:
	v_mov_b64_e32 v[2:3], s[90:91]
	v_mad_i64_i32 v[2:3], s[4:5], v46, s29, v[2:3]
	s_lshl_b32 s74, s17, 1
	v_lshl_add_u64 v[2:3], v[2:3], 0, s[74:75]
	v_mov_b32_e32 v65, v1
	v_lshl_add_u64 v[2:3], v[2:3], 0, v[64:65]
	s_waitcnt vmcnt(0)
	v_mfma_f32_16x16x32_bf16 v[12:15], v[192:195], v[36:39], v[12:15]
	v_cndmask_b32_e64 v0, 0, 1, s[12:13]
	v_cmp_ne_u32_e64 s[10:11], 1, v0
	s_andn2_b64 vcc, exec, s[12:13]
	s_cbranch_vccz .LBB0_643

; DEVINL f32x4 mfma16(bf16x8 a, bf16x8 b, f32x4 c) { return __builtin_amdgcn_mfma_f32_16x16x32_bf16(a, b, c, 0, 0, 0); }
; DEVINL void ssd1_item(const Params& p, int layer, int item, char* smem, int wv) {
;     ...
;     for (int st = 0; st < 8; ++st) {
;       if (st <= LT) {
;         bf16x8 bfm = *(const bf16x8*)(xc + (size_t)(tok0 + st * 16 + fr) * 1536 + 1024 + g * 128 + kc * 32 + fq * 8);
;         G[st] = mfma16(bfm, cf, G[st]);
;       }
.LBB0_621:
	v_mov_b64_e32 v[2:3], s[90:91]
	v_mad_i64_i32 v[2:3], s[6:7], v50, s29, v[2:3]
	s_lshl_b32 s74, s17, 1
	v_lshl_add_u64 v[2:3], v[2:3], 0, s[74:75]
	v_mov_b32_e32 v65, v1
	v_lshl_add_u64 v[2:3], v[2:3], 0, v[64:65]
	s_waitcnt vmcnt(0)
	v_mfma_f32_16x16x32_bf16 v[20:23], v[200:203], v[36:39], v[20:23]
	v_cndmask_b32_e64 v0, 0, 1, s[18:19]
	v_cmp_ne_u32_e64 s[12:13], 1, v0
	s_andn2_b64 vcc, exec, s[18:19]
	s_cbranch_vccz .LBB0_645

; DEVINL f32x4 mfma16(bf16x8 a, bf16x8 b, f32x4 c) { return __builtin_amdgcn_mfma_f32_16x16x32_bf16(a, b, c, 0, 0, 0); }
; DEVINL void ssd1_item(const Params& p, int layer, int item, char* smem, int wv) {
;     ...
;   for (int kc = 0; kc < 4; ++kc) {
;     bf16x8 cf = *(const bf16x8*)(xc + (size_t)(tok0 + LT * 16 + fr) * 1536 + 1280 + g * 128 + kc * 32 + fq * 8);
; #pragma unroll
;     for (int st = 0; st < 8; ++st) {
;       if (st <= LT) {
;         bf16x8 bfm = *(const bf16x8*)(xc + (size_t)(tok0 + st * 16 + fr) * 1536 + 1024 + g * 128 + kc * 32 + fq * 8);
;         G[st] = mfma16(bfm, cf, G[st]);
;       }
.LBB0_623:
	v_mov_b64_e32 v[2:3], s[90:91]
	v_mad_i64_i32 v[2:3], s[14:15], v52, s29, v[2:3]
	s_lshl_b32 s74, s17, 1
	v_lshl_add_u64 v[2:3], v[2:3], 0, s[74:75]
	v_mov_b32_e32 v65, v1
	v_lshl_add_u64 v[2:3], v[2:3], 0, v[64:65]
	s_waitcnt vmcnt(0)
	v_mfma_f32_16x16x32_bf16 v[28:31], v[208:211], v[36:39], v[28:31]
	v_cndmask_b32_e64 v0, 0, 1, s[22:23]
	v_cmp_ne_u32_e64 s[14:15], 1, v0
	s_andn2_b64 vcc, exec, s[22:23]
	s_cbranch_vccz .LBB0_647
.LBB0_624:
	global_load_dwordx4 v[36:39], v[42:43], off offset:2688
	global_load_dwordx4 v[184:187], v[216:217], off offset:2176
	global_load_dwordx4 v[188:191], v[218:219], off offset:2176
	global_load_dwordx4 v[192:195], v[220:221], off offset:2176
	global_load_dwordx4 v[196:199], v[222:223], off offset:2176
	global_load_dwordx4 v[200:203], v[224:225], off offset:2176
	global_load_dwordx4 v[204:207], v[226:227], off offset:2176
	global_load_dwordx4 v[208:211], v[228:229], off offset:2176
	global_load_dwordx4 v[212:215], v[230:231], off offset:2176
	s_and_b64 vcc, exec, s[0:1]
	s_cbranch_vccnz .LBB0_648
.LBB0_625:
	v_mov_b64_e32 v[2:3], s[90:91]
	v_mad_i64_i32 v[2:3], s[18:19], v41, s29, v[2:3]
	s_lshl_b32 s74, s17, 1
	v_lshl_add_u64 v[2:3], v[2:3], 0, s[74:75]
	v_mov_b32_e32 v65, v1
	v_lshl_add_u64 v[2:3], v[2:3], 0, v[64:65]
	s_waitcnt vmcnt(0)
	v_mfma_f32_16x16x32_bf16 v[4:7], v[184:187], v[36:39], v[4:7]
	s_and_b64 vcc, exec, s[8:9]
	s_cbranch_vccz .LBB0_649

; DEVINL f32x4 mfma16(bf16x8 a, bf16x8 b, f32x4 c) { return __builtin_amdgcn_mfma_f32_16x16x32_bf16(a, b, c, 0, 0, 0); }
; DEVINL void ssd1_item(const Params& p, int layer, int item, char* smem, int wv) {
;     ...
;     for (int st = 0; st < 8; ++st) {
;       if (st <= LT) {
;         bf16x8 bfm = *(const bf16x8*)(xc + (size_t)(tok0 + st * 16 + fr) * 1536 + 1024 + g * 128 + kc * 32 + fq * 8);
;         G[st] = mfma16(bfm, cf, G[st]);
;       }
.LBB0_627:
	v_mov_b64_e32 v[2:3], s[90:91]
	v_mad_i64_i32 v[2:3], s[18:19], v46, s29, v[2:3]
	s_lshl_b32 s74, s17, 1
	v_lshl_add_u64 v[2:3], v[2:3], 0, s[74:75]
	v_mov_b32_e32 v65, v1
	v_lshl_add_u64 v[2:3], v[2:3], 0, v[64:65]
	s_waitcnt vmcnt(0)
	v_mfma_f32_16x16x32_bf16 v[12:15], v[192:195], v[36:39], v[12:15]
	s_and_b64 vcc, exec, s[10:11]
	s_cbranch_vccz .LBB0_651

; DEVINL f32x4 mfma16(bf16x8 a, bf16x8 b, f32x4 c) { return __builtin_amdgcn_mfma_f32_16x16x32_bf16(a, b, c, 0, 0, 0); }
; DEVINL void ssd1_item(const Params& p, int layer, int item, char* smem, int wv) {
;     ...
;     for (int st = 0; st < 8; ++st) {
;       if (st <= LT) {
;         bf16x8 bfm = *(const bf16x8*)(xc + (size_t)(tok0 + st * 16 + fr) * 1536 + 1024 + g * 128 + kc * 32 + fq * 8);
;         G[st] = mfma16(bfm, cf, G[st]);
;       }
.LBB0_629:
	v_mov_b64_e32 v[2:3], s[90:91]
	v_mad_i64_i32 v[2:3], s[18:19], v50, s29, v[2:3]
	s_lshl_b32 s74, s17, 1
	v_lshl_add_u64 v[2:3], v[2:3], 0, s[74:75]
	v_mov_b32_e32 v65, v1
	v_lshl_add_u64 v[2:3], v[2:3], 0, v[64:65]
	s_waitcnt vmcnt(0)
	v_mfma_f32_16x16x32_bf16 v[20:23], v[200:203], v[36:39], v[20:23]
	s_and_b64 vcc, exec, s[12:13]
	s_cbranch_vccz .LBB0_653

; DEVINL f32x4 mfma16(bf16x8 a, bf16x8 b, f32x4 c) { return __builtin_amdgcn_mfma_f32_16x16x32_bf16(a, b, c, 0, 0, 0); }
; DEVINL void ssd1_item(const Params& p, int layer, int item, char* smem, int wv) {
;     ...
;   for (int kc = 0; kc < 4; ++kc) {
;     bf16x8 cf = *(const bf16x8*)(xc + (size_t)(tok0 + LT * 16 + fr) * 1536 + 1280 + g * 128 + kc * 32 + fq * 8);
; #pragma unroll
;     for (int st = 0; st < 8; ++st) {
;       if (st <= LT) {
;         bf16x8 bfm = *(const bf16x8*)(xc + (size_t)(tok0 + st * 16 + fr) * 1536 + 1024 + g * 128 + kc * 32 + fq * 8);
;         G[st] = mfma16(bfm, cf, G[st]);
;       }
.LBB0_631:
	v_mov_b64_e32 v[2:3], s[90:91]
	v_mad_i64_i32 v[2:3], s[18:19], v52, s29, v[2:3]
	s_lshl_b32 s74, s17, 1
	v_lshl_add_u64 v[2:3], v[2:3], 0, s[74:75]
	v_mov_b32_e32 v65, v1
	v_lshl_add_u64 v[2:3], v[2:3], 0, v[64:65]
	s_waitcnt vmcnt(0)
	v_mfma_f32_16x16x32_bf16 v[28:31], v[208:211], v[36:39], v[28:31]
	s_and_b64 vcc, exec, s[14:15]
	s_cbranch_vccz .LBB0_655
.LBB0_632:
	global_load_dwordx4 v[36:39], v[42:43], off offset:2752
	global_load_dwordx4 v[184:187], v[216:217], off offset:2240
	global_load_dwordx4 v[188:191], v[218:219], off offset:2240
	global_load_dwordx4 v[192:195], v[220:221], off offset:2240
	global_load_dwordx4 v[196:199], v[222:223], off offset:2240
	global_load_dwordx4 v[200:203], v[224:225], off offset:2240
	global_load_dwordx4 v[204:207], v[226:227], off offset:2240
	global_load_dwordx4 v[208:211], v[228:229], off offset:2240
	global_load_dwordx4 v[212:215], v[230:231], off offset:2240
	s_and_b64 vcc, exec, s[0:1]
	s_cbranch_vccnz .LBB0_656

; DEVINL f32x4 mfma16(bf16x8 a, bf16x8 b, f32x4 c) { return __builtin_amdgcn_mfma_f32_16x16x32_bf16(a, b, c, 0, 0, 0); }
; DEVINL void ssd1_item(const Params& p, int layer, int item, char* smem, int wv) {
;     ...
;     for (int st = 0; st < 8; ++st) {
;       if (st <= LT) {
;         bf16x8 bfm = *(const bf16x8*)(xc + (size_t)(tok0 + st * 16 + fr) * 1536 + 1024 + g * 128 + kc * 32 + fq * 8);
;         G[st] = mfma16(bfm, cf, G[st]);
;       }
.LBB0_635:
	v_mov_b64_e32 v[2:3], s[90:91]
	v_mad_i64_i32 v[2:3], s[8:9], v46, s29, v[2:3]
	s_lshl_b32 s74, s17, 1
	v_lshl_add_u64 v[2:3], v[2:3], 0, s[74:75]
	v_mov_b32_e32 v65, v1
	v_lshl_add_u64 v[2:3], v[2:3], 0, v[64:65]
	s_waitcnt vmcnt(0)
	v_mfma_f32_16x16x32_bf16 v[12:15], v[192:195], v[36:39], v[12:15]
	s_and_b64 vcc, exec, s[10:11]
	s_cbranch_vccz .LBB0_659

; DEVINL f32x4 mfma16(bf16x8 a, bf16x8 b, f32x4 c) { return __builtin_amdgcn_mfma_f32_16x16x32_bf16(a, b, c, 0, 0, 0); }
; DEVINL void ssd1_item(const Params& p, int layer, int item, char* smem, int wv) {
;     ...
;     for (int st = 0; st < 8; ++st) {
;       if (st <= LT) {
;         bf16x8 bfm = *(const bf16x8*)(xc + (size_t)(tok0 + st * 16 + fr) * 1536 + 1024 + g * 128 + kc * 32 + fq * 8);
;         G[st] = mfma16(bfm, cf, G[st]);
;       }
.LBB0_637:
	v_mov_b64_e32 v[2:3], s[90:91]
	v_mad_i64_i32 v[2:3], s[8:9], v50, s29, v[2:3]
	s_lshl_b32 s74, s17, 1
	v_lshl_add_u64 v[2:3], v[2:3], 0, s[74:75]
	v_mov_b32_e32 v65, v1
	v_lshl_add_u64 v[2:3], v[2:3], 0, v[64:65]
	s_waitcnt vmcnt(0)
	v_mfma_f32_16x16x32_bf16 v[20:23], v[200:203], v[36:39], v[20:23]
	s_and_b64 vcc, exec, s[12:13]
	s_cbranch_vccz .LBB0_661

; DEVINL f32x4 mfma16(bf16x8 a, bf16x8 b, f32x4 c) { return __builtin_amdgcn_mfma_f32_16x16x32_bf16(a, b, c, 0, 0, 0); }
; DEVINL void ssd1_item(const Params& p, int layer, int item, char* smem, int wv) {
;     ...
;     for (int st = 0; st < 8; ++st) {
;       if (st <= LT) {
;         bf16x8 bfm = *(const bf16x8*)(xc + (size_t)(tok0 + st * 16 + fr) * 1536 + 1024 + g * 128 + kc * 32 + fq * 8);
;         G[st] = mfma16(bfm, cf, G[st]);
;       }
.LBB0_639:
	v_mov_b64_e32 v[2:3], s[90:91]
	v_mad_i64_i32 v[2:3], s[8:9], v52, s29, v[2:3]
	s_lshl_b32 s74, s17, 1
	v_lshl_add_u64 v[2:3], v[2:3], 0, s[74:75]
	v_mov_b32_e32 v65, v1
	v_lshl_add_u64 v[2:3], v[2:3], 0, v[64:65]
	s_waitcnt vmcnt(0)
	v_mfma_f32_16x16x32_bf16 v[28:31], v[208:211], v[36:39], v[28:31]
	s_and_b64 vcc, exec, s[14:15]
	s_cbranch_vccz .LBB0_663
	s_branch .LBB0_664

; DEVINL f32x4 mfma16(bf16x8 a, bf16x8 b, f32x4 c) { return __builtin_amdgcn_mfma_f32_16x16x32_bf16(a, b, c, 0, 0, 0); }
; DEVINL void ssd1_item(const Params& p, int layer, int item, char* smem, int wv) {
;     ...
;     for (int st = 0; st < 8; ++st) {
;       if (st <= LT) {
;         bf16x8 bfm = *(const bf16x8*)(xc + (size_t)(tok0 + st * 16 + fr) * 1536 + 1024 + g * 128 + kc * 32 + fq * 8);
;         G[st] = mfma16(bfm, cf, G[st]);
;       }
.LBB0_641:
	v_mov_b64_e32 v[2:3], s[90:91]
	v_mad_i64_i32 v[2:3], s[2:3], v45, s29, v[2:3]
	s_lshl_b32 s74, s17, 1
	v_lshl_add_u64 v[2:3], v[2:3], 0, s[74:75]
	v_mov_b32_e32 v65, v1
	v_lshl_add_u64 v[2:3], v[2:3], 0, v[64:65]
	s_waitcnt vmcnt(0)
	v_mfma_f32_16x16x32_bf16 v[8:11], v[188:191], v[36:39], v[8:11]
	v_cndmask_b32_e64 v0, 0, 1, s[6:7]
	v_cmp_ne_u32_e64 s[2:3], 1, v0
	s_andn2_b64 vcc, exec, s[6:7]
	s_cbranch_vccz .LBB0_619

; DEVINL f32x4 mfma16(bf16x8 a, bf16x8 b, f32x4 c) { return __builtin_amdgcn_mfma_f32_16x16x32_bf16(a, b, c, 0, 0, 0); }
; DEVINL void ssd1_item(const Params& p, int layer, int item, char* smem, int wv) {
;     ...
;     for (int st = 0; st < 8; ++st) {
;       if (st <= LT) {
;         bf16x8 bfm = *(const bf16x8*)(xc + (size_t)(tok0 + st * 16 + fr) * 1536 + 1024 + g * 128 + kc * 32 + fq * 8);
;         G[st] = mfma16(bfm, cf, G[st]);
;       }
.LBB0_643:
	v_mov_b64_e32 v[2:3], s[90:91]
	v_mad_i64_i32 v[2:3], s[4:5], v49, s29, v[2:3]
	s_lshl_b32 s74, s17, 1
	v_lshl_add_u64 v[2:3], v[2:3], 0, s[74:75]
	v_mov_b32_e32 v65, v1
	v_lshl_add_u64 v[2:3], v[2:3], 0, v[64:65]
	s_waitcnt vmcnt(0)
	v_mfma_f32_16x16x32_bf16 v[16:19], v[196:199], v[36:39], v[16:19]
	v_cndmask_b32_e64 v0, 0, 1, s[14:15]
	v_cmp_ne_u32_e64 s[4:5], 1, v0
	s_andn2_b64 vcc, exec, s[14:15]
	s_cbranch_vccz .LBB0_621

; DEVINL f32x4 mfma16(bf16x8 a, bf16x8 b, f32x4 c) { return __builtin_amdgcn_mfma_f32_16x16x32_bf16(a, b, c, 0, 0, 0); }
; DEVINL void ssd1_item(const Params& p, int layer, int item, char* smem, int wv) {
;     ...
;     for (int st = 0; st < 8; ++st) {
;       if (st <= LT) {
;         bf16x8 bfm = *(const bf16x8*)(xc + (size_t)(tok0 + st * 16 + fr) * 1536 + 1024 + g * 128 + kc * 32 + fq * 8);
;         G[st] = mfma16(bfm, cf, G[st]);
;       }
.LBB0_645:
	v_mov_b64_e32 v[2:3], s[90:91]
	v_mad_i64_i32 v[2:3], s[6:7], v51, s29, v[2:3]
	s_lshl_b32 s74, s17, 1
	v_lshl_add_u64 v[2:3], v[2:3], 0, s[74:75]
	v_mov_b32_e32 v65, v1
	v_lshl_add_u64 v[2:3], v[2:3], 0, v[64:65]
	s_waitcnt vmcnt(0)
	v_mfma_f32_16x16x32_bf16 v[24:27], v[204:207], v[36:39], v[24:27]
	v_cndmask_b32_e64 v0, 0, 1, s[20:21]
	v_cmp_ne_u32_e64 s[6:7], 1, v0
	s_andn2_b64 vcc, exec, s[20:21]
	s_cbranch_vccz .LBB0_623

; DEVINL f32x4 mfma16(bf16x8 a, bf16x8 b, f32x4 c) { return __builtin_amdgcn_mfma_f32_16x16x32_bf16(a, b, c, 0, 0, 0); }
; DEVINL void ssd1_item(const Params& p, int layer, int item, char* smem, int wv) {
;     ...
;   for (int kc = 0; kc < 4; ++kc) {
;     bf16x8 cf = *(const bf16x8*)(xc + (size_t)(tok0 + LT * 16 + fr) * 1536 + 1280 + g * 128 + kc * 32 + fq * 8);
; #pragma unroll
;     for (int st = 0; st < 8; ++st) {
;       if (st <= LT) {
;         bf16x8 bfm = *(const bf16x8*)(xc + (size_t)(tok0 + st * 16 + fr) * 1536 + 1024 + g * 128 + kc * 32 + fq * 8);
;         G[st] = mfma16(bfm, cf, G[st]);
;       }
.LBB0_647:
	v_mov_b64_e32 v[2:3], s[90:91]
	v_mad_i64_i32 v[2:3], s[18:19], v53, s29, v[2:3]
	s_lshl_b32 s74, s17, 1
	v_lshl_add_u64 v[2:3], v[2:3], 0, s[74:75]
	v_mov_b32_e32 v65, v1
	v_lshl_add_u64 v[2:3], v[2:3], 0, v[64:65]
	s_waitcnt vmcnt(0)
	v_mfma_f32_16x16x32_bf16 v[32:35], v[212:215], v[36:39], v[32:35]
	global_load_dwordx4 v[36:39], v[42:43], off offset:2688
	global_load_dwordx4 v[184:187], v[216:217], off offset:2176
	global_load_dwordx4 v[188:191], v[218:219], off offset:2176
	global_load_dwordx4 v[192:195], v[220:221], off offset:2176
	global_load_dwordx4 v[196:199], v[222:223], off offset:2176
	global_load_dwordx4 v[200:203], v[224:225], off offset:2176
	global_load_dwordx4 v[204:207], v[226:227], off offset:2176
	global_load_dwordx4 v[208:211], v[228:229], off offset:2176
	global_load_dwordx4 v[212:215], v[230:231], off offset:2176
	s_and_b64 vcc, exec, s[0:1]
	s_cbranch_vccz .LBB0_625

; DEVINL f32x4 mfma16(bf16x8 a, bf16x8 b, f32x4 c) { return __builtin_amdgcn_mfma_f32_16x16x32_bf16(a, b, c, 0, 0, 0); }
; DEVINL void ssd1_item(const Params& p, int layer, int item, char* smem, int wv) {
;     ...
;     for (int st = 0; st < 8; ++st) {
;       if (st <= LT) {
;         bf16x8 bfm = *(const bf16x8*)(xc + (size_t)(tok0 + st * 16 + fr) * 1536 + 1024 + g * 128 + kc * 32 + fq * 8);
;         G[st] = mfma16(bfm, cf, G[st]);
;       }
.LBB0_649:
	v_mov_b64_e32 v[2:3], s[90:91]
	v_mad_i64_i32 v[2:3], s[18:19], v45, s29, v[2:3]
	s_lshl_b32 s74, s17, 1
	v_lshl_add_u64 v[2:3], v[2:3], 0, s[74:75]
	v_mov_b32_e32 v65, v1
	v_lshl_add_u64 v[2:3], v[2:3], 0, v[64:65]
	s_waitcnt vmcnt(0)
	v_mfma_f32_16x16x32_bf16 v[8:11], v[188:191], v[36:39], v[8:11]
	s_and_b64 vcc, exec, s[2:3]
	s_cbranch_vccz .LBB0_627

; DEVINL f32x4 mfma16(bf16x8 a, bf16x8 b, f32x4 c) { return __builtin_amdgcn_mfma_f32_16x16x32_bf16(a, b, c, 0, 0, 0); }
; DEVINL void ssd1_item(const Params& p, int layer, int item, char* smem, int wv) {
;     ...
;     for (int st = 0; st < 8; ++st) {
;       if (st <= LT) {
;         bf16x8 bfm = *(const bf16x8*)(xc + (size_t)(tok0 + st * 16 + fr) * 1536 + 1024 + g * 128 + kc * 32 + fq * 8);
;         G[st] = mfma16(bfm, cf, G[st]);
;       }
.LBB0_651:
	v_mov_b64_e32 v[2:3], s[90:91]
	v_mad_i64_i32 v[2:3], s[18:19], v49, s29, v[2:3]
	s_lshl_b32 s74, s17, 1
	v_lshl_add_u64 v[2:3], v[2:3], 0, s[74:75]
	v_mov_b32_e32 v65, v1
	v_lshl_add_u64 v[2:3], v[2:3], 0, v[64:65]
	s_waitcnt vmcnt(0)
	v_mfma_f32_16x16x32_bf16 v[16:19], v[196:199], v[36:39], v[16:19]
	s_and_b64 vcc, exec, s[4:5]
	s_cbranch_vccz .LBB0_629

; DEVINL f32x4 mfma16(bf16x8 a, bf16x8 b, f32x4 c) { return __builtin_amdgcn_mfma_f32_16x16x32_bf16(a, b, c, 0, 0, 0); }
; DEVINL void ssd1_item(const Params& p, int layer, int item, char* smem, int wv) {
;     ...
;     for (int st = 0; st < 8; ++st) {
;       if (st <= LT) {
;         bf16x8 bfm = *(const bf16x8*)(xc + (size_t)(tok0 + st * 16 + fr) * 1536 + 1024 + g * 128 + kc * 32 + fq * 8);
;         G[st] = mfma16(bfm, cf, G[st]);
;       }
.LBB0_653:
	v_mov_b64_e32 v[2:3], s[90:91]
	v_mad_i64_i32 v[2:3], s[18:19], v51, s29, v[2:3]
	s_lshl_b32 s74, s17, 1
	v_lshl_add_u64 v[2:3], v[2:3], 0, s[74:75]
	v_mov_b32_e32 v65, v1
	v_lshl_add_u64 v[2:3], v[2:3], 0, v[64:65]
	s_waitcnt vmcnt(0)
	v_mfma_f32_16x16x32_bf16 v[24:27], v[204:207], v[36:39], v[24:27]
	s_and_b64 vcc, exec, s[6:7]
	s_cbranch_vccz .LBB0_631

; DEVINL f32x4 mfma16(bf16x8 a, bf16x8 b, f32x4 c) { return __builtin_amdgcn_mfma_f32_16x16x32_bf16(a, b, c, 0, 0, 0); }
; DEVINL void ssd1_item(const Params& p, int layer, int item, char* smem, int wv) {
;     ...
;   for (int kc = 0; kc < 4; ++kc) {
;     bf16x8 cf = *(const bf16x8*)(xc + (size_t)(tok0 + LT * 16 + fr) * 1536 + 1280 + g * 128 + kc * 32 + fq * 8);
; #pragma unroll
;     for (int st = 0; st < 8; ++st) {
;       if (st <= LT) {
;         bf16x8 bfm = *(const bf16x8*)(xc + (size_t)(tok0 + st * 16 + fr) * 1536 + 1024 + g * 128 + kc * 32 + fq * 8);
;         G[st] = mfma16(bfm, cf, G[st]);
;       }
.LBB0_655:
	v_mov_b64_e32 v[2:3], s[90:91]
	v_mad_i64_i32 v[2:3], s[18:19], v53, s29, v[2:3]
	s_lshl_b32 s74, s17, 1
	v_lshl_add_u64 v[2:3], v[2:3], 0, s[74:75]
	v_mov_b32_e32 v65, v1
	v_lshl_add_u64 v[2:3], v[2:3], 0, v[64:65]
	s_waitcnt vmcnt(0)
	v_mfma_f32_16x16x32_bf16 v[32:35], v[212:215], v[36:39], v[32:35]
	global_load_dwordx4 v[36:39], v[42:43], off offset:2752
	global_load_dwordx4 v[184:187], v[216:217], off offset:2240
	global_load_dwordx4 v[188:191], v[218:219], off offset:2240
	global_load_dwordx4 v[192:195], v[220:221], off offset:2240
	global_load_dwordx4 v[196:199], v[222:223], off offset:2240
	global_load_dwordx4 v[200:203], v[224:225], off offset:2240
	global_load_dwordx4 v[204:207], v[226:227], off offset:2240
	global_load_dwordx4 v[208:211], v[228:229], off offset:2240
	global_load_dwordx4 v[212:215], v[230:231], off offset:2240
	s_and_b64 vcc, exec, s[0:1]
	s_cbranch_vccz .LBB0_633

; DEVINL f32x4 mfma16(bf16x8 a, bf16x8 b, f32x4 c) { return __builtin_amdgcn_mfma_f32_16x16x32_bf16(a, b, c, 0, 0, 0); }
; DEVINL void ssd1_item(const Params& p, int layer, int item, char* smem, int wv) {
;     ...
;     for (int st = 0; st < 8; ++st) {
;       if (st <= LT) {
;         bf16x8 bfm = *(const bf16x8*)(xc + (size_t)(tok0 + st * 16 + fr) * 1536 + 1024 + g * 128 + kc * 32 + fq * 8);
;         G[st] = mfma16(bfm, cf, G[st]);
;       }
.LBB0_657:
	v_mov_b64_e32 v[2:3], s[90:91]
	v_mad_i64_i32 v[2:3], s[8:9], v45, s29, v[2:3]
	s_lshl_b32 s74, s17, 1
	v_lshl_add_u64 v[2:3], v[2:3], 0, s[74:75]
	v_mov_b32_e32 v65, v1
	v_lshl_add_u64 v[2:3], v[2:3], 0, v[64:65]
	s_waitcnt vmcnt(0)
	v_mfma_f32_16x16x32_bf16 v[8:11], v[188:191], v[36:39], v[8:11]
	s_and_b64 vcc, exec, s[2:3]
	s_cbranch_vccz .LBB0_635

; DEVINL f32x4 mfma16(bf16x8 a, bf16x8 b, f32x4 c) { return __builtin_amdgcn_mfma_f32_16x16x32_bf16(a, b, c, 0, 0, 0); }
; DEVINL void ssd1_item(const Params& p, int layer, int item, char* smem, int wv) {
;     ...
;     for (int st = 0; st < 8; ++st) {
;       if (st <= LT) {
;         bf16x8 bfm = *(const bf16x8*)(xc + (size_t)(tok0 + st * 16 + fr) * 1536 + 1024 + g * 128 + kc * 32 + fq * 8);
;         G[st] = mfma16(bfm, cf, G[st]);
;       }
.LBB0_659:
	v_mov_b64_e32 v[2:3], s[90:91]
	v_mad_i64_i32 v[2:3], s[8:9], v49, s29, v[2:3]
	s_lshl_b32 s74, s17, 1
	v_lshl_add_u64 v[2:3], v[2:3], 0, s[74:75]
	v_mov_b32_e32 v65, v1
	v_lshl_add_u64 v[2:3], v[2:3], 0, v[64:65]
	s_waitcnt vmcnt(0)
	v_mfma_f32_16x16x32_bf16 v[16:19], v[196:199], v[36:39], v[16:19]
	s_and_b64 vcc, exec, s[4:5]
	s_cbranch_vccz .LBB0_637

; DEVINL f32x4 mfma16(bf16x8 a, bf16x8 b, f32x4 c) { return __builtin_amdgcn_mfma_f32_16x16x32_bf16(a, b, c, 0, 0, 0); }
; DEVINL void ssd1_item(const Params& p, int layer, int item, char* smem, int wv) {
;     ...
;     for (int st = 0; st < 8; ++st) {
;       if (st <= LT) {
;         bf16x8 bfm = *(const bf16x8*)(xc + (size_t)(tok0 + st * 16 + fr) * 1536 + 1024 + g * 128 + kc * 32 + fq * 8);
;         G[st] = mfma16(bfm, cf, G[st]);
;       }
.LBB0_661:
	v_mov_b64_e32 v[2:3], s[90:91]
	v_mad_i64_i32 v[2:3], s[8:9], v51, s29, v[2:3]
	s_lshl_b32 s74, s17, 1
	v_lshl_add_u64 v[2:3], v[2:3], 0, s[74:75]
	v_mov_b32_e32 v65, v1
	v_lshl_add_u64 v[2:3], v[2:3], 0, v[64:65]
	s_waitcnt vmcnt(0)
	v_mfma_f32_16x16x32_bf16 v[24:27], v[204:207], v[36:39], v[24:27]
	s_and_b64 vcc, exec, s[6:7]
	s_cbranch_vccz .LBB0_639

; DEVINL f32x4 mfma16(bf16x8 a, bf16x8 b, f32x4 c) { return __builtin_amdgcn_mfma_f32_16x16x32_bf16(a, b, c, 0, 0, 0); }
; DEVINL void ssd1_item(const Params& p, int layer, int item, char* smem, int wv) {
;     ...
;     for (int st = 0; st < 8; ++st) {
;       if (st <= LT) {
;         bf16x8 bfm = *(const bf16x8*)(xc + (size_t)(tok0 + st * 16 + fr) * 1536 + 1024 + g * 128 + kc * 32 + fq * 8);
;         G[st] = mfma16(bfm, cf, G[st]);
;       }
.LBB0_663:
	v_mov_b64_e32 v[2:3], s[90:91]
	v_mad_i64_i32 v[2:3], s[8:9], v53, s29, v[2:3]
	s_lshl_b32 s74, s17, 1
	v_lshl_add_u64 v[2:3], v[2:3], 0, s[74:75]
	v_mov_b32_e32 v65, v1
	v_lshl_add_u64 v[2:3], v[2:3], 0, v[64:65]
	s_waitcnt vmcnt(0)
	v_mfma_f32_16x16x32_bf16 v[32:35], v[212:215], v[36:39], v[32:35]

; DEVINL float shup(float v, int off, int lane) { return __int_as_float(__builtin_amdgcn_ds_bpermute(((lane - off) & 63) << 2, __float_as_int(v))); }
; DEVINL void ssd1_item(const Params& p, int layer, int item, char* smem, int wv) {
;     ...
;     int hh = wid, hd = g * 8 + hh;
;     float a = -expf(p.a_log[layer * 16 + hd]);
;     float v0 = dtf[(size_t)(tok0 + 2 * lane) * 16 + hd] * a;
;     float v1 = dtf[(size_t)(tok0 + 2 * lane + 1) * 16 + hd] * a;
;     float s = v0 + v1;
; #pragma unroll
;     for (int off = 1; off < 64; off <<= 1) { float tt = shup(s, off, lane); if (lane >= off) s += tt; }
;     float ex = s - (v0 + v1);
;     ac[hh * 128 + 2 * lane] = ex + v0; ac[hh * 128 + 2 * lane + 1] = ex + v0 + v1;
; DEVINL void phase_mix(const Params& p, int layer, char* smem, int wv, int rep) {
;     ...
;       int it = next_item(ctr, smem, wv);
;       if (it >= 256) break;
.LBB0_1613:
	s_or_b64 exec, exec, s[2:3]
	s_waitcnt lgkmcnt(0)
	s_barrier
	ds_read_b32 v0, v124
	s_movk_i32 s0, 0xff
	s_mov_b64 s[2:3], -1
	s_waitcnt lgkmcnt(0)
	v_cmp_lt_i32_e32 vcc, s0, v0
	v_readfirstlane_b32 s1, v0
	s_cbranch_vccnz .LBB0_1608
	v_mov_b32_e32 v22, v176
	s_and_b32 s28, s1, 1
	v_readfirstlane_b32 s0, v22
	s_ashr_i32 s26, s0, 6
	s_bfe_u32 s0, s1, 0x50001
	s_ashr_i32 s1, s1, 6
	s_lshl_b32 s2, s1, 12
	s_lshl_b32 s3, s0, 7
	s_lshl_b32 s88, s28, 3
	s_or_b32 s27, s3, s2
	s_add_i32 s2, s26, s88
	v_readlane_b32 s8, v254, 2
	s_ashr_i32 s3, s2, 31
	v_readlane_b32 s12, v254, 6
	v_readlane_b32 s13, v254, 7
	v_readlane_b32 s14, v254, 8
	v_readlane_b32 s15, v254, 9
	v_readlane_b32 s20, v254, 14
	v_readlane_b32 s21, v254, 15
	s_lshl_b64 s[4:5], s[2:3], 2
	v_readlane_b32 s22, v254, 16
	v_readlane_b32 s23, v254, 17
	s_mov_b64 s[12:13], s[20:21]
	s_add_u32 s4, s12, s4
	s_addc_u32 s5, s13, s5
	global_load_dword v0, v1, s[4:5] offset:64
	v_and_b32_e32 v127, 63, v22
	v_lshlrev_b32_e32 v23, 1, v127
	v_or_b32_e32 v2, s27, v23
	v_ashrrev_i32_e32 v3, 31, v2
	v_lshl_add_u64 v[4:5], v[2:3], 4, s[2:3]
	v_or_b32_e32 v2, 1, v2
	v_ashrrev_i32_e32 v3, 31, v2
	v_readlane_b32 s4, v254, 52
	v_lshl_add_u64 v[2:3], v[2:3], 4, s[2:3]
	v_readlane_b32 s5, v254, 53
	v_lshlrev_b64 v[2:3], 2, v[2:3]
	v_lshlrev_b64 v[4:5], 2, v[4:5]
	v_lshl_add_u64 v[8:9], s[4:5], 0, v[2:3]
	v_lshl_add_u64 v[6:7], s[4:5], 0, v[4:5]
	global_load_dword v8, v[8:9], off
	s_nop 0
	global_load_dword v9, v[6:7], off
	s_mov_b32 s2, 0x3fb8aa3b
	s_mov_b32 s3, 0xc2ce8ed0
	s_mov_b32 s4, 0x42b17218
	v_mov_b64_e32 v[18:19], s[90:91]
	v_or_b32_e32 v40, s27, v127
	v_readlane_b32 s18, v254, 12
	v_readlane_b32 s19, v254, 13
	s_lshl_b32 s18, s26, 4
	s_lshl_b32 s80, s28, 8
	s_ashr_i32 s19, s18, 31
	v_or_b32_e32 v57, 64, v127
	v_and_b32_e32 v56, 15, v22
	v_add_u32_e32 v48, 0, v23
	v_bfe_u32 v47, v22, 4, 2
	v_lshlrev_b32_e32 v44, 3, v47
	v_or_b32_e32 v41, s27, v56
	s_waitcnt vmcnt(10)
	v_lshlrev_b32_e32 v64, 1, v44
	v_readlane_b32 s9, v254, 3
	v_readlane_b32 s10, v254, 4
	v_readlane_b32 s11, v254, 5
	v_readlane_b32 s16, v254, 10
	v_readlane_b32 s17, v254, 11
	s_mov_b64 s[14:15], s[22:23]
	s_waitcnt vmcnt(2)
	v_mul_f32_e32 v6, 0x3fb8aa3b, v0
	v_fma_f32 v7, v0, s2, -v6
	v_rndne_f32_e32 v10, v6
	v_fmac_f32_e32 v7, 0x32a5705f, v0
	v_sub_f32_e32 v6, v6, v10
	v_add_f32_e32 v6, v6, v7
	v_cvt_i32_f32_e32 v10, v10
	v_exp_f32_e32 v6, v6
	v_cmp_ngt_f32_e32 vcc, s3, v0
	v_lshlrev_b32_e32 v7, 2, v22
	v_add_u32_e32 v11, 0xfc, v7
	v_ldexp_f32 v6, v6, v10
	v_cndmask_b32_e32 v6, 0, v6, vcc
	v_cmp_nlt_f32_e32 vcc, s4, v0
	v_and_b32_e32 v11, 0xfc, v11
	v_add_u32_e32 v10, 0xf8, v7
	v_cndmask_b32_e32 v0, v125, v6, vcc
	s_waitcnt vmcnt(1)
	v_mul_f32_e32 v6, v8, v0
	s_waitcnt vmcnt(0)
	v_fma_f32 v12, v9, -v0, -v6
	ds_bpermute_b32 v6, v11, v12
	v_cmp_eq_u32_e32 vcc, 0, v127
	v_and_b32_e32 v10, 0xfc, v10
	v_add_u32_e32 v11, 0xf0, v7
	v_and_b32_e32 v11, 0xfc, v11
	s_waitcnt lgkmcnt(0)
	v_add_f32_e32 v6, v12, v6
	v_cndmask_b32_e32 v6, v6, v12, vcc
	ds_bpermute_b32 v10, v10, v6
	v_cmp_gt_u32_e32 vcc, 2, v127
	s_movk_i32 s2, 0x80
	v_add_u32_e32 v13, 0xc0, v7
	v_bitop3_b32 v14, v7, s2, v126 bitop3:0x6c
	s_waitcnt lgkmcnt(0)
	v_add_f32_e32 v10, v6, v10
	v_cndmask_b32_e32 v6, v10, v6, vcc
	ds_bpermute_b32 v10, v11, v6
	v_add_u32_e32 v11, 0xe0, v7
	v_cmp_gt_u32_e32 vcc, 4, v127
	v_and_b32_e32 v7, 0xfc, v11
	v_and_b32_e32 v13, 0xfc, v13
	s_waitcnt lgkmcnt(0)
	v_add_f32_e32 v10, v6, v10
	v_cndmask_b32_e32 v10, v10, v6, vcc
	ds_bpermute_b32 v11, v7, v10
	v_cmp_gt_u32_e32 vcc, 8, v127
	v_mad_i64_i32 v[6:7], s[2:3], v40, s29, v[18:19]
	v_readlane_b32 s2, v254, 56
	s_waitcnt lgkmcnt(0)
	v_add_f32_e32 v11, v10, v11
	v_cndmask_b32_e32 v10, v11, v10, vcc
	ds_bpermute_b32 v11, v13, v10
	v_cmp_gt_u32_e32 vcc, 16, v127
	v_readlane_b32 s3, v254, 57
	v_lshl_add_u64 v[6:7], v[6:7], 0, s[80:81]
	s_waitcnt lgkmcnt(0)
	v_add_f32_e32 v11, v10, v11
	v_cndmask_b32_e32 v13, v11, v10, vcc
	ds_bpermute_b32 v14, v14, v13
	v_lshl_add_u64 v[4:5], s[2:3], 0, v[4:5]
	v_lshl_add_u64 v[2:3], s[2:3], 0, v[2:3]
	s_lshl_b64 s[2:3], s[18:19], 1
	v_lshl_add_u64 v[10:11], v[6:7], 0, s[2:3]
	s_waitcnt lgkmcnt(0)
; DEVINL f32x4 mfma16(bf16x8 a, bf16x8 b, f32x4 c) { return __builtin_amdgcn_mfma_f32_16x16x32_bf16(a, b, c, 0, 0, 0); }
; DEVINL float shup(float v, int off, int lane) { return __int_as_float(__builtin_amdgcn_ds_bpermute(((lane - off) & 63) << 2, __float_as_int(v))); }
; DEVINL void ssd1_item(const Params& p, int layer, int item, char* smem, int wv) {
;     ...
;     for (int off = 1; off < 64; off <<= 1) { float tt = shup(s, off, lane); if (lane >= off) s += tt; }
;     float ex = s - (v0 + v1);
;     ac[hh * 128 + 2 * lane] = ex + v0; ac[hh * 128 + 2 * lane + 1] = ex + v0 + v1;
;     acumg[(size_t)(tok0 + 2 * lane) * 16 + hd] = ex + v0;
;     acumg[(size_t)(tok0 + 2 * lane + 1) * 16 + hd] = ex + v0 + v1;
;   }
; #pragma unroll
;   for (int i = 0; i < 4; ++i) {
;     const int combo = wid * 4 + i; const int nc = combo >> 1, s = lane + 64 * (combo & 1);
;     bf16x8 raw = *(const bf16x8*)(xc + (size_t)(tok0 + s) * 1536 + 1024 + g * 128 + nc * 8);
; #pragma unroll
;     for (int k = 0; k < 8; ++k) Bt[(nc * 8 + k) * 136 + s] = (u16)raw[k];
;   }
;   f32x4 G[8];
; #pragma unroll
;   for (int st = 0; st < 8; ++st) G[st] = f32x4{0.f, 0.f, 0.f, 0.f};
; #pragma unroll
;   for (int kc = 0; kc < 4; ++kc) {
;     bf16x8 cf = *(const bf16x8*)(xc + (size_t)(tok0 + LT * 16 + fr) * 1536 + 1280 + g * 128 + kc * 32 + fq * 8);
; #pragma unroll
;     for (int st = 0; st < 8; ++st) {
;       if (st <= LT) {
;         bf16x8 bfm = *(const bf16x8*)(xc + (size_t)(tok0 + st * 16 + fr) * 1536 + 1024 + g * 128 + kc * 32 + fq * 8);
;         G[st] = mfma16(bfm, cf, G[st]);
;       }
;     }
;   }
	v_add_f32_e32 v6, v13, v14
	v_cmp_gt_u32_e32 vcc, 32, v127
	s_lshl_b32 s19, s28, 7
	s_nop 0
	v_cndmask_b32_e32 v6, v6, v13, vcc
	v_sub_f32_e32 v6, v6, v12
	v_fma_f32 v20, v9, -v0, v6
	v_fma_f32 v21, v8, -v0, v20
	v_or_b32_e32 v0, s27, v57
	v_mad_i64_i32 v[6:7], s[4:5], v0, s29, v[18:19]
	v_lshl_add_u64 v[6:7], v[6:7], 0, s[80:81]
	v_lshl_add_u64 v[14:15], v[6:7], 0, s[2:3]
	s_add_i32 s2, s18, s27
	v_or_b32_e32 v24, s2, v56
	v_mad_i64_i32 v[18:19], s[2:3], v24, s29, v[18:19]
	v_and_b32_e32 v0, 48, v22
	v_lshl_add_u64 v[18:19], v[18:19], 0, s[80:81]
	global_store_dword v[4:5], v20, off
	global_store_dword v[2:3], v21, off
	v_lshl_add_u64 v[42:43], v[18:19], 0, v[0:1]
	s_lshl_b32 s98, s19, 1
	s_mov_b32 s99, 0
	v_mov_b32_e32 v232, v64
	v_mov_b32_e32 v233, 0
	v_mov_b32_e32 v234, v41
	v_mov_b64_e32 v[216:217], s[90:91]
	v_mad_i64_i32 v[216:217], s[100:101], v234, s29, v[216:217]
	v_lshl_add_u64 v[216:217], v[216:217], 0, s[98:99]
	v_lshl_add_u64 v[216:217], v[216:217], 0, v[232:233]
	v_or_b32_e32 v234, 16, v41
	v_mov_b64_e32 v[218:219], s[90:91]
	v_mad_i64_i32 v[218:219], s[100:101], v234, s29, v[218:219]
	v_lshl_add_u64 v[218:219], v[218:219], 0, s[98:99]
	v_lshl_add_u64 v[218:219], v[218:219], 0, v[232:233]
	v_or_b32_e32 v234, 32, v41
	v_mov_b64_e32 v[220:221], s[90:91]
	v_mad_i64_i32 v[220:221], s[100:101], v234, s29, v[220:221]
	v_lshl_add_u64 v[220:221], v[220:221], 0, s[98:99]
	v_lshl_add_u64 v[220:221], v[220:221], 0, v[232:233]
	v_or_b32_e32 v234, 48, v41
	v_mov_b64_e32 v[222:223], s[90:91]
	v_mad_i64_i32 v[222:223], s[100:101], v234, s29, v[222:223]
	v_lshl_add_u64 v[222:223], v[222:223], 0, s[98:99]
	v_lshl_add_u64 v[222:223], v[222:223], 0, v[232:233]
	v_or_b32_e32 v234, 64, v41
	v_mov_b64_e32 v[224:225], s[90:91]
	v_mad_i64_i32 v[224:225], s[100:101], v234, s29, v[224:225]
	v_lshl_add_u64 v[224:225], v[224:225], 0, s[98:99]
	v_lshl_add_u64 v[224:225], v[224:225], 0, v[232:233]
	v_or_b32_e32 v234, 80, v41
	v_mov_b64_e32 v[226:227], s[90:91]
	v_mad_i64_i32 v[226:227], s[100:101], v234, s29, v[226:227]
	v_lshl_add_u64 v[226:227], v[226:227], 0, s[98:99]
	v_lshl_add_u64 v[226:227], v[226:227], 0, v[232:233]
	v_or_b32_e32 v234, 96, v41
	v_mov_b64_e32 v[228:229], s[90:91]
	v_mad_i64_i32 v[228:229], s[100:101], v234, s29, v[228:229]
	v_lshl_add_u64 v[228:229], v[228:229], 0, s[98:99]
	v_lshl_add_u64 v[228:229], v[228:229], 0, v[232:233]
	v_or_b32_e32 v234, 112, v41
	v_mov_b64_e32 v[230:231], s[90:91]
	v_mad_i64_i32 v[230:231], s[100:101], v234, s29, v[230:231]
	v_lshl_add_u64 v[230:231], v[230:231], 0, s[98:99]
	v_lshl_add_u64 v[230:231], v[230:231], 0, v[232:233]
	global_load_dwordx4 v[2:5], v[10:11], off offset:2048
	global_load_dwordx4 v[6:9], v[14:15], off offset:2048
	s_nop 0
	global_load_dwordx4 v[10:13], v[10:11], off offset:2064
	s_nop 0
	global_load_dwordx4 v[14:17], v[14:15], off offset:2064
	s_mul_i32 s2, s26, 0x1100
	global_load_dwordx4 v[32:35], v[42:43], off offset:2560
	v_add_u32_e32 v0, s2, v48
	s_lshl_b32 s2, s26, 9
	s_add_i32 s2, s2, 0
	s_or_b32 s3, s18, 8
	v_lshl_add_u32 v18, v127, 3, s2
	s_cmp_gt_i32 s26, -1
	s_mulk_i32 s3, 0x110
	v_add_u32_e32 v18, 0x19800, v18
	s_cselect_b64 s[4:5], -1, 0
	s_cmp_lt_i32 s26, 0
	v_add_u32_e32 v19, s3, v48
	ds_write_b64 v18, v[20:21]
	s_waitcnt vmcnt(4)
	ds_write_b16 v0, v2
	ds_write_b16_d16_hi v0, v2 offset:272
	ds_write_b16 v0, v3 offset:544
	ds_write_b16_d16_hi v0, v3 offset:816
	ds_write_b16 v0, v4 offset:1088
	ds_write_b16_d16_hi v0, v4 offset:1360
	ds_write_b16 v0, v5 offset:1632
	ds_write_b16_d16_hi v0, v5 offset:1904
	s_waitcnt vmcnt(3)
	ds_write_b16 v0, v6 offset:128
	ds_write_b16_d16_hi v0, v6 offset:400
	ds_write_b16 v0, v7 offset:672
	ds_write_b16_d16_hi v0, v7 offset:944
	ds_write_b16 v0, v8 offset:1216
	ds_write_b16_d16_hi v0, v8 offset:1488
	ds_write_b16 v0, v9 offset:1760
	ds_write_b16_d16_hi v0, v9 offset:2032
	s_waitcnt vmcnt(2)
	ds_write_b16 v19, v10
	ds_write_b16_d16_hi v0, v10 offset:2448
	ds_write_b16 v0, v11 offset:2720
	ds_write_b16_d16_hi v0, v11 offset:2992
	ds_write_b16 v0, v12 offset:3264
	ds_write_b16_d16_hi v0, v12 offset:3536
	ds_write_b16 v0, v13 offset:3808
	ds_write_b16_d16_hi v0, v13 offset:4080
	s_waitcnt vmcnt(1)
	ds_write_b16 v19, v14 offset:128
	ds_write_b16_d16_hi v0, v14 offset:2576
	ds_write_b16 v0, v15 offset:2848
	ds_write_b16_d16_hi v0, v15 offset:3120
	ds_write_b16 v0, v16 offset:3392
	ds_write_b16_d16_hi v0, v16 offset:3664
	ds_write_b16 v0, v17 offset:3936
	ds_write_b16_d16_hi v0, v17 offset:4208
	global_load_dwordx4 v[184:187], v[216:217], off offset:2048
	global_load_dwordx4 v[188:191], v[218:219], off offset:2048
	global_load_dwordx4 v[192:195], v[220:221], off offset:2048
	global_load_dwordx4 v[196:199], v[222:223], off offset:2048
	global_load_dwordx4 v[200:203], v[224:225], off offset:2048
	global_load_dwordx4 v[204:207], v[226:227], off offset:2048
	global_load_dwordx4 v[208:211], v[228:229], off offset:2048
	global_load_dwordx4 v[212:215], v[230:231], off offset:2048
	s_cbranch_scc1 .LBB0_1616
	v_mov_b64_e32 v[2:3], s[90:91]
	v_mad_i64_i32 v[2:3], s[2:3], v41, s29, v[2:3]
	s_lshl_b32 s80, s19, 1
	v_lshl_add_u64 v[2:3], v[2:3], 0, s[80:81]
	v_mov_b32_e32 v65, v1
	v_lshl_add_u64 v[2:3], v[2:3], 0, v[64:65]
	s_waitcnt vmcnt(0)
	v_mfma_f32_16x16x32_bf16 v[4:7], v[184:187], v[32:35], 0
	s_branch .LBB0_1617

; DEVINL f32x4 mfma16(bf16x8 a, bf16x8 b, f32x4 c) { return __builtin_amdgcn_mfma_f32_16x16x32_bf16(a, b, c, 0, 0, 0); }
; DEVINL void ssd1_item(const Params& p, int layer, int item, char* smem, int wv) {
;     ...
;     for (int st = 0; st < 8; ++st) {
;       if (st <= LT) {
;         bf16x8 bfm = *(const bf16x8*)(xc + (size_t)(tok0 + st * 16 + fr) * 1536 + 1024 + g * 128 + kc * 32 + fq * 8);
;         G[st] = mfma16(bfm, cf, G[st]);
;       }
.LBB0_1617:
	s_cmp_gt_i32 s26, 0
	s_cselect_b64 s[6:7], -1, 0
	s_cmp_lt_i32 s26, 1
	v_or_b32_e32 v45, 16, v41
	s_cbranch_scc1 .LBB0_1619
	v_mov_b64_e32 v[2:3], s[90:91]
	v_mad_i64_i32 v[2:3], s[2:3], v45, s29, v[2:3]
	s_lshl_b32 s80, s19, 1
	v_lshl_add_u64 v[2:3], v[2:3], 0, s[80:81]
	v_mov_b32_e32 v65, v1
	v_lshl_add_u64 v[2:3], v[2:3], 0, v[64:65]
	s_waitcnt vmcnt(0)
	v_mfma_f32_16x16x32_bf16 v[8:11], v[188:191], v[32:35], 0
	s_branch .LBB0_1620

; DEVINL f32x4 mfma16(bf16x8 a, bf16x8 b, f32x4 c) { return __builtin_amdgcn_mfma_f32_16x16x32_bf16(a, b, c, 0, 0, 0); }
; DEVINL void ssd1_item(const Params& p, int layer, int item, char* smem, int wv) {
;     ...
;     for (int st = 0; st < 8; ++st) {
;       if (st <= LT) {
;         bf16x8 bfm = *(const bf16x8*)(xc + (size_t)(tok0 + st * 16 + fr) * 1536 + 1024 + g * 128 + kc * 32 + fq * 8);
;         G[st] = mfma16(bfm, cf, G[st]);
;       }
.LBB0_1620:
	s_cmp_gt_i32 s26, 1
	s_cselect_b64 s[8:9], -1, 0
	s_cmp_lt_i32 s26, 2
	v_or_b32_e32 v46, 32, v41
	s_cbranch_scc1 .LBB0_1622
	v_mov_b64_e32 v[2:3], s[90:91]
	v_mad_i64_i32 v[2:3], s[2:3], v46, s29, v[2:3]
	s_lshl_b32 s80, s19, 1
	v_lshl_add_u64 v[2:3], v[2:3], 0, s[80:81]
	v_mov_b32_e32 v65, v1
	v_lshl_add_u64 v[2:3], v[2:3], 0, v[64:65]
	s_waitcnt vmcnt(0)
	v_mfma_f32_16x16x32_bf16 v[12:15], v[192:195], v[32:35], 0
	s_branch .LBB0_1623

; DEVINL f32x4 mfma16(bf16x8 a, bf16x8 b, f32x4 c) { return __builtin_amdgcn_mfma_f32_16x16x32_bf16(a, b, c, 0, 0, 0); }
; DEVINL void ssd1_item(const Params& p, int layer, int item, char* smem, int wv) {
;     ...
;     for (int st = 0; st < 8; ++st) {
;       if (st <= LT) {
;         bf16x8 bfm = *(const bf16x8*)(xc + (size_t)(tok0 + st * 16 + fr) * 1536 + 1024 + g * 128 + kc * 32 + fq * 8);
;         G[st] = mfma16(bfm, cf, G[st]);
;       }
.LBB0_1623:
	s_cmp_gt_i32 s26, 2
	s_cselect_b64 s[14:15], -1, 0
	s_cmp_lt_i32 s26, 3
	v_or_b32_e32 v49, 48, v41
	s_cbranch_scc1 .LBB0_1625
	v_mov_b64_e32 v[2:3], s[90:91]
	v_mad_i64_i32 v[2:3], s[2:3], v49, s29, v[2:3]
	s_lshl_b32 s80, s19, 1
	v_lshl_add_u64 v[2:3], v[2:3], 0, s[80:81]
	v_mov_b32_e32 v65, v1
	v_lshl_add_u64 v[2:3], v[2:3], 0, v[64:65]
	s_waitcnt vmcnt(0)
	v_mfma_f32_16x16x32_bf16 v[16:19], v[196:199], v[32:35], 0
	s_branch .LBB0_1626

; DEVINL f32x4 mfma16(bf16x8 a, bf16x8 b, f32x4 c) { return __builtin_amdgcn_mfma_f32_16x16x32_bf16(a, b, c, 0, 0, 0); }
; DEVINL void ssd1_item(const Params& p, int layer, int item, char* smem, int wv) {
;     ...
;     for (int st = 0; st < 8; ++st) {
;       if (st <= LT) {
;         bf16x8 bfm = *(const bf16x8*)(xc + (size_t)(tok0 + st * 16 + fr) * 1536 + 1024 + g * 128 + kc * 32 + fq * 8);
;         G[st] = mfma16(bfm, cf, G[st]);
;       }
.LBB0_1626:
	s_cmp_gt_i32 s26, 3
	s_cselect_b64 s[16:17], -1, 0
	s_cmp_lt_i32 s26, 4
	v_or_b32_e32 v50, 64, v41
	s_cbranch_scc1 .LBB0_1628
	v_mov_b64_e32 v[2:3], s[90:91]
	v_mad_i64_i32 v[2:3], s[2:3], v50, s29, v[2:3]
	s_lshl_b32 s80, s19, 1
	v_lshl_add_u64 v[2:3], v[2:3], 0, s[80:81]
	v_mov_b32_e32 v65, v1
	v_lshl_add_u64 v[2:3], v[2:3], 0, v[64:65]
	s_waitcnt vmcnt(0)
	v_mfma_f32_16x16x32_bf16 v[20:23], v[200:203], v[32:35], 0
	s_branch .LBB0_1629

; DEVINL f32x4 mfma16(bf16x8 a, bf16x8 b, f32x4 c) { return __builtin_amdgcn_mfma_f32_16x16x32_bf16(a, b, c, 0, 0, 0); }
; DEVINL void ssd1_item(const Params& p, int layer, int item, char* smem, int wv) {
;     ...
;     for (int st = 0; st < 8; ++st) {
;       if (st <= LT) {
;         bf16x8 bfm = *(const bf16x8*)(xc + (size_t)(tok0 + st * 16 + fr) * 1536 + 1024 + g * 128 + kc * 32 + fq * 8);
;         G[st] = mfma16(bfm, cf, G[st]);
;       }
.LBB0_1629:
	s_cmp_gt_i32 s26, 4
	s_cselect_b64 s[20:21], -1, 0
	s_cmp_lt_i32 s26, 5
	v_or_b32_e32 v51, 0x50, v41
	s_cbranch_scc1 .LBB0_1631
	v_mov_b64_e32 v[2:3], s[90:91]
	v_mad_i64_i32 v[2:3], s[2:3], v51, s29, v[2:3]
	s_lshl_b32 s80, s19, 1
	v_lshl_add_u64 v[2:3], v[2:3], 0, s[80:81]
	v_mov_b32_e32 v65, v1
	v_lshl_add_u64 v[2:3], v[2:3], 0, v[64:65]
	s_waitcnt vmcnt(0)
	v_mfma_f32_16x16x32_bf16 v[24:27], v[204:207], v[32:35], 0
	s_branch .LBB0_1632

; DEVINL f32x4 mfma16(bf16x8 a, bf16x8 b, f32x4 c) { return __builtin_amdgcn_mfma_f32_16x16x32_bf16(a, b, c, 0, 0, 0); }
; DEVINL void ssd1_item(const Params& p, int layer, int item, char* smem, int wv) {
;     ...
;     for (int st = 0; st < 8; ++st) {
;       if (st <= LT) {
;         bf16x8 bfm = *(const bf16x8*)(xc + (size_t)(tok0 + st * 16 + fr) * 1536 + 1024 + g * 128 + kc * 32 + fq * 8);
;         G[st] = mfma16(bfm, cf, G[st]);
;       }
.LBB0_1632:
	s_cmp_gt_i32 s26, 5
	s_cselect_b64 s[22:23], -1, 0
	s_cmp_lt_i32 s26, 6
	v_or_b32_e32 v52, 0x60, v41
	s_cbranch_scc1 .LBB0_1634
	v_mov_b64_e32 v[2:3], s[90:91]
	v_mad_i64_i32 v[2:3], s[2:3], v52, s29, v[2:3]
	s_lshl_b32 s80, s19, 1
	v_lshl_add_u64 v[2:3], v[2:3], 0, s[80:81]
	v_mov_b32_e32 v65, v1
	v_lshl_add_u64 v[2:3], v[2:3], 0, v[64:65]
	s_waitcnt vmcnt(0)
	v_mfma_f32_16x16x32_bf16 v[28:31], v[208:211], v[32:35], 0
	s_branch .LBB0_1635

; DEVINL f32x4 mfma16(bf16x8 a, bf16x8 b, f32x4 c) { return __builtin_amdgcn_mfma_f32_16x16x32_bf16(a, b, c, 0, 0, 0); }
; DEVINL void ssd1_item(const Params& p, int layer, int item, char* smem, int wv) {
;     ...
;     for (int st = 0; st < 8; ++st) {
;       if (st <= LT) {
;         bf16x8 bfm = *(const bf16x8*)(xc + (size_t)(tok0 + st * 16 + fr) * 1536 + 1024 + g * 128 + kc * 32 + fq * 8);
;         G[st] = mfma16(bfm, cf, G[st]);
;       }
.LBB0_1635:
	s_cmp_gt_i32 s26, 6
	s_cselect_b64 s[24:25], -1, 0
	s_cmp_lt_i32 s26, 7
	v_or_b32_e32 v53, 0x70, v41
	s_cbranch_scc1 .LBB0_1637
	v_mov_b64_e32 v[2:3], s[90:91]
	v_mad_i64_i32 v[2:3], s[2:3], v53, s29, v[2:3]
	s_lshl_b32 s80, s19, 1
	v_lshl_add_u64 v[2:3], v[2:3], 0, s[80:81]
	v_mov_b32_e32 v65, v1
	v_lshl_add_u64 v[2:3], v[2:3], 0, v[64:65]
	s_waitcnt vmcnt(0)
	v_mfma_f32_16x16x32_bf16 v[32:35], v[212:215], v[32:35], 0
	s_branch .LBB0_1638

; DEVINL f32x4 mfma16(bf16x8 a, bf16x8 b, f32x4 c) { return __builtin_amdgcn_mfma_f32_16x16x32_bf16(a, b, c, 0, 0, 0); }
; DEVINL void ssd1_item(const Params& p, int layer, int item, char* smem, int wv) {
;     ...
;   for (int kc = 0; kc < 4; ++kc) {
;     bf16x8 cf = *(const bf16x8*)(xc + (size_t)(tok0 + LT * 16 + fr) * 1536 + 1280 + g * 128 + kc * 32 + fq * 8);
; #pragma unroll
;     for (int st = 0; st < 8; ++st) {
;       if (st <= LT) {
;         bf16x8 bfm = *(const bf16x8*)(xc + (size_t)(tok0 + st * 16 + fr) * 1536 + 1024 + g * 128 + kc * 32 + fq * 8);
;         G[st] = mfma16(bfm, cf, G[st]);
;       }
.LBB0_1638:
	global_load_dwordx4 v[36:39], v[42:43], off offset:2624
	global_load_dwordx4 v[184:187], v[216:217], off offset:2112
	global_load_dwordx4 v[188:191], v[218:219], off offset:2112
	global_load_dwordx4 v[192:195], v[220:221], off offset:2112
	global_load_dwordx4 v[196:199], v[222:223], off offset:2112
	global_load_dwordx4 v[200:203], v[224:225], off offset:2112
	global_load_dwordx4 v[204:207], v[226:227], off offset:2112
	global_load_dwordx4 v[208:211], v[228:229], off offset:2112
	global_load_dwordx4 v[212:215], v[230:231], off offset:2112
	v_cndmask_b32_e64 v0, 0, 1, s[4:5]
	v_cmp_ne_u32_e64 s[2:3], 1, v0
	s_andn2_b64 vcc, exec, s[4:5]
	s_cbranch_vccnz .LBB0_1662
	v_mov_b64_e32 v[2:3], s[90:91]
	v_mad_i64_i32 v[2:3], s[4:5], v41, s29, v[2:3]
	s_lshl_b32 s80, s19, 1
	v_lshl_add_u64 v[2:3], v[2:3], 0, s[80:81]
	v_mov_b32_e32 v65, v1
	v_lshl_add_u64 v[2:3], v[2:3], 0, v[64:65]
	s_waitcnt vmcnt(0)
	v_mfma_f32_16x16x32_bf16 v[4:7], v[184:187], v[36:39], v[4:7]
	v_cndmask_b32_e64 v0, 0, 1, s[6:7]
	v_cmp_ne_u32_e64 s[10:11], 1, v0
	s_andn2_b64 vcc, exec, s[6:7]
	s_cbranch_vccz .LBB0_1663

; DEVINL f32x4 mfma16(bf16x8 a, bf16x8 b, f32x4 c) { return __builtin_amdgcn_mfma_f32_16x16x32_bf16(a, b, c, 0, 0, 0); }
; DEVINL void ssd1_item(const Params& p, int layer, int item, char* smem, int wv) {
;     ...
;     for (int st = 0; st < 8; ++st) {
;       if (st <= LT) {
;         bf16x8 bfm = *(const bf16x8*)(xc + (size_t)(tok0 + st * 16 + fr) * 1536 + 1024 + g * 128 + kc * 32 + fq * 8);
;         G[st] = mfma16(bfm, cf, G[st]);
;       }
.LBB0_1641:
	v_mov_b64_e32 v[2:3], s[90:91]
	v_mad_i64_i32 v[2:3], s[6:7], v46, s29, v[2:3]
	s_lshl_b32 s80, s19, 1
	v_lshl_add_u64 v[2:3], v[2:3], 0, s[80:81]
	v_mov_b32_e32 v65, v1
	v_lshl_add_u64 v[2:3], v[2:3], 0, v[64:65]
	s_waitcnt vmcnt(0)
	v_mfma_f32_16x16x32_bf16 v[12:15], v[192:195], v[36:39], v[12:15]
	v_cndmask_b32_e64 v0, 0, 1, s[14:15]
	v_cmp_ne_u32_e64 s[12:13], 1, v0
	s_andn2_b64 vcc, exec, s[14:15]
	s_cbranch_vccz .LBB0_1665

; DEVINL f32x4 mfma16(bf16x8 a, bf16x8 b, f32x4 c) { return __builtin_amdgcn_mfma_f32_16x16x32_bf16(a, b, c, 0, 0, 0); }
; DEVINL void ssd1_item(const Params& p, int layer, int item, char* smem, int wv) {
;     ...
;     for (int st = 0; st < 8; ++st) {
;       if (st <= LT) {
;         bf16x8 bfm = *(const bf16x8*)(xc + (size_t)(tok0 + st * 16 + fr) * 1536 + 1024 + g * 128 + kc * 32 + fq * 8);
;         G[st] = mfma16(bfm, cf, G[st]);
;       }
.LBB0_1643:
	v_mov_b64_e32 v[2:3], s[90:91]
	v_mad_i64_i32 v[2:3], s[8:9], v50, s29, v[2:3]
	s_lshl_b32 s80, s19, 1
	v_lshl_add_u64 v[2:3], v[2:3], 0, s[80:81]
	v_mov_b32_e32 v65, v1
	v_lshl_add_u64 v[2:3], v[2:3], 0, v[64:65]
	s_waitcnt vmcnt(0)
	v_mfma_f32_16x16x32_bf16 v[20:23], v[200:203], v[36:39], v[20:23]
	v_cndmask_b32_e64 v0, 0, 1, s[20:21]
	v_cmp_ne_u32_e64 s[14:15], 1, v0
	s_andn2_b64 vcc, exec, s[20:21]
	s_cbranch_vccz .LBB0_1667

; DEVINL f32x4 mfma16(bf16x8 a, bf16x8 b, f32x4 c) { return __builtin_amdgcn_mfma_f32_16x16x32_bf16(a, b, c, 0, 0, 0); }
; DEVINL void ssd1_item(const Params& p, int layer, int item, char* smem, int wv) {
;     ...
;   for (int kc = 0; kc < 4; ++kc) {
;     bf16x8 cf = *(const bf16x8*)(xc + (size_t)(tok0 + LT * 16 + fr) * 1536 + 1280 + g * 128 + kc * 32 + fq * 8);
; #pragma unroll
;     for (int st = 0; st < 8; ++st) {
;       if (st <= LT) {
;         bf16x8 bfm = *(const bf16x8*)(xc + (size_t)(tok0 + st * 16 + fr) * 1536 + 1024 + g * 128 + kc * 32 + fq * 8);
;         G[st] = mfma16(bfm, cf, G[st]);
;       }
.LBB0_1645:
	v_mov_b64_e32 v[2:3], s[90:91]
	v_mad_i64_i32 v[2:3], s[16:17], v52, s29, v[2:3]
	s_lshl_b32 s80, s19, 1
	v_lshl_add_u64 v[2:3], v[2:3], 0, s[80:81]
	v_mov_b32_e32 v65, v1
	v_lshl_add_u64 v[2:3], v[2:3], 0, v[64:65]
	s_waitcnt vmcnt(0)
	v_mfma_f32_16x16x32_bf16 v[28:31], v[208:211], v[36:39], v[28:31]
	v_cndmask_b32_e64 v0, 0, 1, s[24:25]
	v_cmp_ne_u32_e64 s[16:17], 1, v0
	s_andn2_b64 vcc, exec, s[24:25]
	s_cbranch_vccz .LBB0_1669
.LBB0_1646:
	global_load_dwordx4 v[36:39], v[42:43], off offset:2688
	global_load_dwordx4 v[184:187], v[216:217], off offset:2176
	global_load_dwordx4 v[188:191], v[218:219], off offset:2176
	global_load_dwordx4 v[192:195], v[220:221], off offset:2176
	global_load_dwordx4 v[196:199], v[222:223], off offset:2176
	global_load_dwordx4 v[200:203], v[224:225], off offset:2176
	global_load_dwordx4 v[204:207], v[226:227], off offset:2176
	global_load_dwordx4 v[208:211], v[228:229], off offset:2176
	global_load_dwordx4 v[212:215], v[230:231], off offset:2176
	s_and_b64 vcc, exec, s[2:3]
	s_cbranch_vccnz .LBB0_1670
.LBB0_1647:
	v_mov_b64_e32 v[2:3], s[90:91]
	v_mad_i64_i32 v[2:3], s[20:21], v41, s29, v[2:3]
	s_lshl_b32 s80, s19, 1
	v_lshl_add_u64 v[2:3], v[2:3], 0, s[80:81]
	v_mov_b32_e32 v65, v1
	v_lshl_add_u64 v[2:3], v[2:3], 0, v[64:65]
	s_waitcnt vmcnt(0)
	v_mfma_f32_16x16x32_bf16 v[4:7], v[184:187], v[36:39], v[4:7]
	s_and_b64 vcc, exec, s[10:11]
	s_cbranch_vccz .LBB0_1671

; DEVINL f32x4 mfma16(bf16x8 a, bf16x8 b, f32x4 c) { return __builtin_amdgcn_mfma_f32_16x16x32_bf16(a, b, c, 0, 0, 0); }
; DEVINL void ssd1_item(const Params& p, int layer, int item, char* smem, int wv) {
;     ...
;     for (int st = 0; st < 8; ++st) {
;       if (st <= LT) {
;         bf16x8 bfm = *(const bf16x8*)(xc + (size_t)(tok0 + st * 16 + fr) * 1536 + 1024 + g * 128 + kc * 32 + fq * 8);
;         G[st] = mfma16(bfm, cf, G[st]);
;       }
.LBB0_1649:
	v_mov_b64_e32 v[2:3], s[90:91]
	v_mad_i64_i32 v[2:3], s[20:21], v46, s29, v[2:3]
	s_lshl_b32 s80, s19, 1
	v_lshl_add_u64 v[2:3], v[2:3], 0, s[80:81]
	v_mov_b32_e32 v65, v1
	v_lshl_add_u64 v[2:3], v[2:3], 0, v[64:65]
	s_waitcnt vmcnt(0)
	v_mfma_f32_16x16x32_bf16 v[12:15], v[192:195], v[36:39], v[12:15]
	s_and_b64 vcc, exec, s[12:13]
	s_cbranch_vccz .LBB0_1673

; DEVINL f32x4 mfma16(bf16x8 a, bf16x8 b, f32x4 c) { return __builtin_amdgcn_mfma_f32_16x16x32_bf16(a, b, c, 0, 0, 0); }
; DEVINL void ssd1_item(const Params& p, int layer, int item, char* smem, int wv) {
;     ...
;     for (int st = 0; st < 8; ++st) {
;       if (st <= LT) {
;         bf16x8 bfm = *(const bf16x8*)(xc + (size_t)(tok0 + st * 16 + fr) * 1536 + 1024 + g * 128 + kc * 32 + fq * 8);
;         G[st] = mfma16(bfm, cf, G[st]);
;       }
.LBB0_1651:
	v_mov_b64_e32 v[2:3], s[90:91]
	v_mad_i64_i32 v[2:3], s[20:21], v50, s29, v[2:3]
	s_lshl_b32 s80, s19, 1
	v_lshl_add_u64 v[2:3], v[2:3], 0, s[80:81]
	v_mov_b32_e32 v65, v1
	v_lshl_add_u64 v[2:3], v[2:3], 0, v[64:65]
	s_waitcnt vmcnt(0)
	v_mfma_f32_16x16x32_bf16 v[20:23], v[200:203], v[36:39], v[20:23]
	s_and_b64 vcc, exec, s[14:15]
	s_cbranch_vccz .LBB0_1675

; DEVINL f32x4 mfma16(bf16x8 a, bf16x8 b, f32x4 c) { return __builtin_amdgcn_mfma_f32_16x16x32_bf16(a, b, c, 0, 0, 0); }
; DEVINL void ssd1_item(const Params& p, int layer, int item, char* smem, int wv) {
;     ...
;   for (int kc = 0; kc < 4; ++kc) {
;     bf16x8 cf = *(const bf16x8*)(xc + (size_t)(tok0 + LT * 16 + fr) * 1536 + 1280 + g * 128 + kc * 32 + fq * 8);
; #pragma unroll
;     for (int st = 0; st < 8; ++st) {
;       if (st <= LT) {
;         bf16x8 bfm = *(const bf16x8*)(xc + (size_t)(tok0 + st * 16 + fr) * 1536 + 1024 + g * 128 + kc * 32 + fq * 8);
;         G[st] = mfma16(bfm, cf, G[st]);
;       }
.LBB0_1653:
	v_mov_b64_e32 v[2:3], s[90:91]
	v_mad_i64_i32 v[2:3], s[20:21], v52, s29, v[2:3]
	s_lshl_b32 s80, s19, 1
	v_lshl_add_u64 v[2:3], v[2:3], 0, s[80:81]
	v_mov_b32_e32 v65, v1
	v_lshl_add_u64 v[2:3], v[2:3], 0, v[64:65]
	s_waitcnt vmcnt(0)
	v_mfma_f32_16x16x32_bf16 v[28:31], v[208:211], v[36:39], v[28:31]
	s_and_b64 vcc, exec, s[16:17]
	s_cbranch_vccz .LBB0_1677
.LBB0_1654:
	global_load_dwordx4 v[36:39], v[42:43], off offset:2752
	global_load_dwordx4 v[184:187], v[216:217], off offset:2240
	global_load_dwordx4 v[188:191], v[218:219], off offset:2240
	global_load_dwordx4 v[192:195], v[220:221], off offset:2240
	global_load_dwordx4 v[196:199], v[222:223], off offset:2240
	global_load_dwordx4 v[200:203], v[224:225], off offset:2240
	global_load_dwordx4 v[204:207], v[226:227], off offset:2240
	global_load_dwordx4 v[208:211], v[228:229], off offset:2240
	global_load_dwordx4 v[212:215], v[230:231], off offset:2240
	s_and_b64 vcc, exec, s[2:3]
	s_cbranch_vccnz .LBB0_1678

; DEVINL f32x4 mfma16(bf16x8 a, bf16x8 b, f32x4 c) { return __builtin_amdgcn_mfma_f32_16x16x32_bf16(a, b, c, 0, 0, 0); }
; DEVINL void ssd1_item(const Params& p, int layer, int item, char* smem, int wv) {
;     ...
;     for (int st = 0; st < 8; ++st) {
;       if (st <= LT) {
;         bf16x8 bfm = *(const bf16x8*)(xc + (size_t)(tok0 + st * 16 + fr) * 1536 + 1024 + g * 128 + kc * 32 + fq * 8);
;         G[st] = mfma16(bfm, cf, G[st]);
;       }
.LBB0_1657:
	v_mov_b64_e32 v[2:3], s[90:91]
	v_mad_i64_i32 v[2:3], s[10:11], v46, s29, v[2:3]
	s_lshl_b32 s80, s19, 1
	v_lshl_add_u64 v[2:3], v[2:3], 0, s[80:81]
	v_mov_b32_e32 v65, v1
	v_lshl_add_u64 v[2:3], v[2:3], 0, v[64:65]
	s_waitcnt vmcnt(0)
	v_mfma_f32_16x16x32_bf16 v[12:15], v[192:195], v[36:39], v[12:15]
	s_and_b64 vcc, exec, s[12:13]
	s_cbranch_vccz .LBB0_1681

; DEVINL f32x4 mfma16(bf16x8 a, bf16x8 b, f32x4 c) { return __builtin_amdgcn_mfma_f32_16x16x32_bf16(a, b, c, 0, 0, 0); }
; DEVINL void ssd1_item(const Params& p, int layer, int item, char* smem, int wv) {
;     ...
;     for (int st = 0; st < 8; ++st) {
;       if (st <= LT) {
;         bf16x8 bfm = *(const bf16x8*)(xc + (size_t)(tok0 + st * 16 + fr) * 1536 + 1024 + g * 128 + kc * 32 + fq * 8);
;         G[st] = mfma16(bfm, cf, G[st]);
;       }
.LBB0_1659:
	v_mov_b64_e32 v[2:3], s[90:91]
	v_mad_i64_i32 v[2:3], s[10:11], v50, s29, v[2:3]
	s_lshl_b32 s80, s19, 1
	v_lshl_add_u64 v[2:3], v[2:3], 0, s[80:81]
	v_mov_b32_e32 v65, v1
	v_lshl_add_u64 v[2:3], v[2:3], 0, v[64:65]
	s_waitcnt vmcnt(0)
	v_mfma_f32_16x16x32_bf16 v[20:23], v[200:203], v[36:39], v[20:23]
	s_and_b64 vcc, exec, s[14:15]
	s_cbranch_vccz .LBB0_1683

; DEVINL f32x4 mfma16(bf16x8 a, bf16x8 b, f32x4 c) { return __builtin_amdgcn_mfma_f32_16x16x32_bf16(a, b, c, 0, 0, 0); }
; DEVINL void ssd1_item(const Params& p, int layer, int item, char* smem, int wv) {
;     ...
;     for (int st = 0; st < 8; ++st) {
;       if (st <= LT) {
;         bf16x8 bfm = *(const bf16x8*)(xc + (size_t)(tok0 + st * 16 + fr) * 1536 + 1024 + g * 128 + kc * 32 + fq * 8);
;         G[st] = mfma16(bfm, cf, G[st]);
;       }
.LBB0_1661:
	v_mov_b64_e32 v[2:3], s[90:91]
	v_mad_i64_i32 v[2:3], s[10:11], v52, s29, v[2:3]
	s_lshl_b32 s80, s19, 1
	v_lshl_add_u64 v[2:3], v[2:3], 0, s[80:81]
	v_mov_b32_e32 v65, v1
	v_lshl_add_u64 v[2:3], v[2:3], 0, v[64:65]
	s_waitcnt vmcnt(0)
	v_mfma_f32_16x16x32_bf16 v[28:31], v[208:211], v[36:39], v[28:31]
	s_and_b64 vcc, exec, s[16:17]
	s_cbranch_vccz .LBB0_1685
	s_branch .LBB0_1686

; DEVINL f32x4 mfma16(bf16x8 a, bf16x8 b, f32x4 c) { return __builtin_amdgcn_mfma_f32_16x16x32_bf16(a, b, c, 0, 0, 0); }
; DEVINL void ssd1_item(const Params& p, int layer, int item, char* smem, int wv) {
;     ...
;     for (int st = 0; st < 8; ++st) {
;       if (st <= LT) {
;         bf16x8 bfm = *(const bf16x8*)(xc + (size_t)(tok0 + st * 16 + fr) * 1536 + 1024 + g * 128 + kc * 32 + fq * 8);
;         G[st] = mfma16(bfm, cf, G[st]);
;       }
.LBB0_1663:
	v_mov_b64_e32 v[2:3], s[90:91]
	v_mad_i64_i32 v[2:3], s[4:5], v45, s29, v[2:3]
	s_lshl_b32 s80, s19, 1
	v_lshl_add_u64 v[2:3], v[2:3], 0, s[80:81]
	v_mov_b32_e32 v65, v1
	v_lshl_add_u64 v[2:3], v[2:3], 0, v[64:65]
	s_waitcnt vmcnt(0)
	v_mfma_f32_16x16x32_bf16 v[8:11], v[188:191], v[36:39], v[8:11]
	v_cndmask_b32_e64 v0, 0, 1, s[8:9]
	v_cmp_ne_u32_e64 s[4:5], 1, v0
	s_andn2_b64 vcc, exec, s[8:9]
	s_cbranch_vccz .LBB0_1641

; DEVINL f32x4 mfma16(bf16x8 a, bf16x8 b, f32x4 c) { return __builtin_amdgcn_mfma_f32_16x16x32_bf16(a, b, c, 0, 0, 0); }
; DEVINL void ssd1_item(const Params& p, int layer, int item, char* smem, int wv) {
;     ...
;     for (int st = 0; st < 8; ++st) {
;       if (st <= LT) {
;         bf16x8 bfm = *(const bf16x8*)(xc + (size_t)(tok0 + st * 16 + fr) * 1536 + 1024 + g * 128 + kc * 32 + fq * 8);
;         G[st] = mfma16(bfm, cf, G[st]);
;       }
.LBB0_1665:
	v_mov_b64_e32 v[2:3], s[90:91]
	v_mad_i64_i32 v[2:3], s[6:7], v49, s29, v[2:3]
	s_lshl_b32 s80, s19, 1
	v_lshl_add_u64 v[2:3], v[2:3], 0, s[80:81]
	v_mov_b32_e32 v65, v1
	v_lshl_add_u64 v[2:3], v[2:3], 0, v[64:65]
	s_waitcnt vmcnt(0)
	v_mfma_f32_16x16x32_bf16 v[16:19], v[196:199], v[36:39], v[16:19]
	v_cndmask_b32_e64 v0, 0, 1, s[16:17]
	v_cmp_ne_u32_e64 s[6:7], 1, v0
	s_andn2_b64 vcc, exec, s[16:17]
	s_cbranch_vccz .LBB0_1643

; DEVINL f32x4 mfma16(bf16x8 a, bf16x8 b, f32x4 c) { return __builtin_amdgcn_mfma_f32_16x16x32_bf16(a, b, c, 0, 0, 0); }
; DEVINL void ssd1_item(const Params& p, int layer, int item, char* smem, int wv) {
;     ...
;     for (int st = 0; st < 8; ++st) {
;       if (st <= LT) {
;         bf16x8 bfm = *(const bf16x8*)(xc + (size_t)(tok0 + st * 16 + fr) * 1536 + 1024 + g * 128 + kc * 32 + fq * 8);
;         G[st] = mfma16(bfm, cf, G[st]);
;       }
.LBB0_1667:
	v_mov_b64_e32 v[2:3], s[90:91]
	v_mad_i64_i32 v[2:3], s[8:9], v51, s29, v[2:3]
	s_lshl_b32 s80, s19, 1
	v_lshl_add_u64 v[2:3], v[2:3], 0, s[80:81]
	v_mov_b32_e32 v65, v1
	v_lshl_add_u64 v[2:3], v[2:3], 0, v[64:65]
	s_waitcnt vmcnt(0)
	v_mfma_f32_16x16x32_bf16 v[24:27], v[204:207], v[36:39], v[24:27]
	v_cndmask_b32_e64 v0, 0, 1, s[22:23]
	v_cmp_ne_u32_e64 s[8:9], 1, v0
	s_andn2_b64 vcc, exec, s[22:23]
	s_cbranch_vccz .LBB0_1645

; DEVINL f32x4 mfma16(bf16x8 a, bf16x8 b, f32x4 c) { return __builtin_amdgcn_mfma_f32_16x16x32_bf16(a, b, c, 0, 0, 0); }
; DEVINL void ssd1_item(const Params& p, int layer, int item, char* smem, int wv) {
;     ...
;   for (int kc = 0; kc < 4; ++kc) {
;     bf16x8 cf = *(const bf16x8*)(xc + (size_t)(tok0 + LT * 16 + fr) * 1536 + 1280 + g * 128 + kc * 32 + fq * 8);
; #pragma unroll
;     for (int st = 0; st < 8; ++st) {
;       if (st <= LT) {
;         bf16x8 bfm = *(const bf16x8*)(xc + (size_t)(tok0 + st * 16 + fr) * 1536 + 1024 + g * 128 + kc * 32 + fq * 8);
;         G[st] = mfma16(bfm, cf, G[st]);
;       }
.LBB0_1669:
	v_mov_b64_e32 v[2:3], s[90:91]
	v_mad_i64_i32 v[2:3], s[20:21], v53, s29, v[2:3]
	s_lshl_b32 s80, s19, 1
	v_lshl_add_u64 v[2:3], v[2:3], 0, s[80:81]
	v_mov_b32_e32 v65, v1
	v_lshl_add_u64 v[2:3], v[2:3], 0, v[64:65]
	s_waitcnt vmcnt(0)
	v_mfma_f32_16x16x32_bf16 v[32:35], v[212:215], v[36:39], v[32:35]
	global_load_dwordx4 v[36:39], v[42:43], off offset:2688
	global_load_dwordx4 v[184:187], v[216:217], off offset:2176
	global_load_dwordx4 v[188:191], v[218:219], off offset:2176
	global_load_dwordx4 v[192:195], v[220:221], off offset:2176
	global_load_dwordx4 v[196:199], v[222:223], off offset:2176
	global_load_dwordx4 v[200:203], v[224:225], off offset:2176
	global_load_dwordx4 v[204:207], v[226:227], off offset:2176
	global_load_dwordx4 v[208:211], v[228:229], off offset:2176
	global_load_dwordx4 v[212:215], v[230:231], off offset:2176
	s_and_b64 vcc, exec, s[2:3]
	s_cbranch_vccz .LBB0_1647

; DEVINL f32x4 mfma16(bf16x8 a, bf16x8 b, f32x4 c) { return __builtin_amdgcn_mfma_f32_16x16x32_bf16(a, b, c, 0, 0, 0); }
; DEVINL void ssd1_item(const Params& p, int layer, int item, char* smem, int wv) {
;     ...
;     for (int st = 0; st < 8; ++st) {
;       if (st <= LT) {
;         bf16x8 bfm = *(const bf16x8*)(xc + (size_t)(tok0 + st * 16 + fr) * 1536 + 1024 + g * 128 + kc * 32 + fq * 8);
;         G[st] = mfma16(bfm, cf, G[st]);
;       }
.LBB0_1671:
	v_mov_b64_e32 v[2:3], s[90:91]
	v_mad_i64_i32 v[2:3], s[20:21], v45, s29, v[2:3]
	s_lshl_b32 s80, s19, 1
	v_lshl_add_u64 v[2:3], v[2:3], 0, s[80:81]
	v_mov_b32_e32 v65, v1
	v_lshl_add_u64 v[2:3], v[2:3], 0, v[64:65]
	s_waitcnt vmcnt(0)
	v_mfma_f32_16x16x32_bf16 v[8:11], v[188:191], v[36:39], v[8:11]
	s_and_b64 vcc, exec, s[4:5]
	s_cbranch_vccz .LBB0_1649

; DEVINL f32x4 mfma16(bf16x8 a, bf16x8 b, f32x4 c) { return __builtin_amdgcn_mfma_f32_16x16x32_bf16(a, b, c, 0, 0, 0); }
; DEVINL void ssd1_item(const Params& p, int layer, int item, char* smem, int wv) {
;     ...
;     for (int st = 0; st < 8; ++st) {
;       if (st <= LT) {
;         bf16x8 bfm = *(const bf16x8*)(xc + (size_t)(tok0 + st * 16 + fr) * 1536 + 1024 + g * 128 + kc * 32 + fq * 8);
;         G[st] = mfma16(bfm, cf, G[st]);
;       }
.LBB0_1673:
	v_mov_b64_e32 v[2:3], s[90:91]
	v_mad_i64_i32 v[2:3], s[20:21], v49, s29, v[2:3]
	s_lshl_b32 s80, s19, 1
	v_lshl_add_u64 v[2:3], v[2:3], 0, s[80:81]
	v_mov_b32_e32 v65, v1
	v_lshl_add_u64 v[2:3], v[2:3], 0, v[64:65]
	s_waitcnt vmcnt(0)
	v_mfma_f32_16x16x32_bf16 v[16:19], v[196:199], v[36:39], v[16:19]
	s_and_b64 vcc, exec, s[6:7]
	s_cbranch_vccz .LBB0_1651

; DEVINL f32x4 mfma16(bf16x8 a, bf16x8 b, f32x4 c) { return __builtin_amdgcn_mfma_f32_16x16x32_bf16(a, b, c, 0, 0, 0); }
; DEVINL void ssd1_item(const Params& p, int layer, int item, char* smem, int wv) {
;     ...
;     for (int st = 0; st < 8; ++st) {
;       if (st <= LT) {
;         bf16x8 bfm = *(const bf16x8*)(xc + (size_t)(tok0 + st * 16 + fr) * 1536 + 1024 + g * 128 + kc * 32 + fq * 8);
;         G[st] = mfma16(bfm, cf, G[st]);
;       }
.LBB0_1675:
	v_mov_b64_e32 v[2:3], s[90:91]
	v_mad_i64_i32 v[2:3], s[20:21], v51, s29, v[2:3]
	s_lshl_b32 s80, s19, 1
	v_lshl_add_u64 v[2:3], v[2:3], 0, s[80:81]
	v_mov_b32_e32 v65, v1
	v_lshl_add_u64 v[2:3], v[2:3], 0, v[64:65]
	s_waitcnt vmcnt(0)
	v_mfma_f32_16x16x32_bf16 v[24:27], v[204:207], v[36:39], v[24:27]
	s_and_b64 vcc, exec, s[8:9]
	s_cbranch_vccz .LBB0_1653

; DEVINL f32x4 mfma16(bf16x8 a, bf16x8 b, f32x4 c) { return __builtin_amdgcn_mfma_f32_16x16x32_bf16(a, b, c, 0, 0, 0); }
; DEVINL void ssd1_item(const Params& p, int layer, int item, char* smem, int wv) {
;     ...
;   for (int kc = 0; kc < 4; ++kc) {
;     bf16x8 cf = *(const bf16x8*)(xc + (size_t)(tok0 + LT * 16 + fr) * 1536 + 1280 + g * 128 + kc * 32 + fq * 8);
; #pragma unroll
;     for (int st = 0; st < 8; ++st) {
;       if (st <= LT) {
;         bf16x8 bfm = *(const bf16x8*)(xc + (size_t)(tok0 + st * 16 + fr) * 1536 + 1024 + g * 128 + kc * 32 + fq * 8);
;         G[st] = mfma16(bfm, cf, G[st]);
;       }
;     }
;   }
.LBB0_1677:
	v_mov_b64_e32 v[2:3], s[90:91]
	v_mad_i64_i32 v[2:3], s[20:21], v53, s29, v[2:3]
	s_lshl_b32 s80, s19, 1
	v_lshl_add_u64 v[2:3], v[2:3], 0, s[80:81]
	v_mov_b32_e32 v65, v1
	v_lshl_add_u64 v[2:3], v[2:3], 0, v[64:65]
	s_waitcnt vmcnt(0)
	v_mfma_f32_16x16x32_bf16 v[32:35], v[212:215], v[36:39], v[32:35]
	global_load_dwordx4 v[36:39], v[42:43], off offset:2752
	global_load_dwordx4 v[184:187], v[216:217], off offset:2240
	global_load_dwordx4 v[188:191], v[218:219], off offset:2240
	global_load_dwordx4 v[192:195], v[220:221], off offset:2240
	global_load_dwordx4 v[196:199], v[222:223], off offset:2240
	global_load_dwordx4 v[200:203], v[224:225], off offset:2240
	global_load_dwordx4 v[204:207], v[226:227], off offset:2240
	global_load_dwordx4 v[208:211], v[228:229], off offset:2240
	global_load_dwordx4 v[212:215], v[230:231], off offset:2240
	s_and_b64 vcc, exec, s[2:3]
	s_cbranch_vccz .LBB0_1655

; DEVINL f32x4 mfma16(bf16x8 a, bf16x8 b, f32x4 c) { return __builtin_amdgcn_mfma_f32_16x16x32_bf16(a, b, c, 0, 0, 0); }
; DEVINL void ssd1_item(const Params& p, int layer, int item, char* smem, int wv) {
;     ...
;   for (int kc = 0; kc < 4; ++kc) {
;     bf16x8 cf = *(const bf16x8*)(xc + (size_t)(tok0 + LT * 16 + fr) * 1536 + 1280 + g * 128 + kc * 32 + fq * 8);
; #pragma unroll
;     for (int st = 0; st < 8; ++st) {
;       if (st <= LT) {
;         bf16x8 bfm = *(const bf16x8*)(xc + (size_t)(tok0 + st * 16 + fr) * 1536 + 1024 + g * 128 + kc * 32 + fq * 8);
;         G[st] = mfma16(bfm, cf, G[st]);
;       }
;     }
;   }
.LBB0_1679:
	v_mov_b64_e32 v[2:3], s[90:91]
	v_mad_i64_i32 v[2:3], s[10:11], v45, s29, v[2:3]
	s_lshl_b32 s80, s19, 1
	v_lshl_add_u64 v[2:3], v[2:3], 0, s[80:81]
	v_mov_b32_e32 v65, v1
	v_lshl_add_u64 v[2:3], v[2:3], 0, v[64:65]
	s_waitcnt vmcnt(0)
	v_mfma_f32_16x16x32_bf16 v[8:11], v[188:191], v[36:39], v[8:11]
	s_and_b64 vcc, exec, s[4:5]
	s_cbranch_vccz .LBB0_1657

; DEVINL f32x4 mfma16(bf16x8 a, bf16x8 b, f32x4 c) { return __builtin_amdgcn_mfma_f32_16x16x32_bf16(a, b, c, 0, 0, 0); }
; DEVINL void ssd1_item(const Params& p, int layer, int item, char* smem, int wv) {
;     ...
;   for (int kc = 0; kc < 4; ++kc) {
;     bf16x8 cf = *(const bf16x8*)(xc + (size_t)(tok0 + LT * 16 + fr) * 1536 + 1280 + g * 128 + kc * 32 + fq * 8);
; #pragma unroll
;     for (int st = 0; st < 8; ++st) {
;       if (st <= LT) {
;         bf16x8 bfm = *(const bf16x8*)(xc + (size_t)(tok0 + st * 16 + fr) * 1536 + 1024 + g * 128 + kc * 32 + fq * 8);
;         G[st] = mfma16(bfm, cf, G[st]);
;       }
;     }
;   }
.LBB0_1681:
	v_mov_b64_e32 v[2:3], s[90:91]
	v_mad_i64_i32 v[2:3], s[10:11], v49, s29, v[2:3]
	s_lshl_b32 s80, s19, 1
	v_lshl_add_u64 v[2:3], v[2:3], 0, s[80:81]
	v_mov_b32_e32 v65, v1
	v_lshl_add_u64 v[2:3], v[2:3], 0, v[64:65]
	s_waitcnt vmcnt(0)
	v_mfma_f32_16x16x32_bf16 v[16:19], v[196:199], v[36:39], v[16:19]
	s_and_b64 vcc, exec, s[6:7]
	s_cbranch_vccz .LBB0_1659

; DEVINL f32x4 mfma16(bf16x8 a, bf16x8 b, f32x4 c) { return __builtin_amdgcn_mfma_f32_16x16x32_bf16(a, b, c, 0, 0, 0); }
; DEVINL void ssd1_item(const Params& p, int layer, int item, char* smem, int wv) {
;     ...
;   for (int kc = 0; kc < 4; ++kc) {
;     bf16x8 cf = *(const bf16x8*)(xc + (size_t)(tok0 + LT * 16 + fr) * 1536 + 1280 + g * 128 + kc * 32 + fq * 8);
; #pragma unroll
;     for (int st = 0; st < 8; ++st) {
;       if (st <= LT) {
;         bf16x8 bfm = *(const bf16x8*)(xc + (size_t)(tok0 + st * 16 + fr) * 1536 + 1024 + g * 128 + kc * 32 + fq * 8);
;         G[st] = mfma16(bfm, cf, G[st]);
;       }
;     }
;   }
.LBB0_1683:
	v_mov_b64_e32 v[2:3], s[90:91]
	v_mad_i64_i32 v[2:3], s[10:11], v51, s29, v[2:3]
	s_lshl_b32 s80, s19, 1
	v_lshl_add_u64 v[2:3], v[2:3], 0, s[80:81]
	v_mov_b32_e32 v65, v1
	v_lshl_add_u64 v[2:3], v[2:3], 0, v[64:65]
	s_waitcnt vmcnt(0)
	v_mfma_f32_16x16x32_bf16 v[24:27], v[204:207], v[36:39], v[24:27]
	s_and_b64 vcc, exec, s[8:9]
	s_cbranch_vccz .LBB0_1661

; DEVINL f32x4 mfma16(bf16x8 a, bf16x8 b, f32x4 c) { return __builtin_amdgcn_mfma_f32_16x16x32_bf16(a, b, c, 0, 0, 0); }
; DEVINL void ssd1_item(const Params& p, int layer, int item, char* smem, int wv) {
;     ...
;   for (int kc = 0; kc < 4; ++kc) {
;     bf16x8 cf = *(const bf16x8*)(xc + (size_t)(tok0 + LT * 16 + fr) * 1536 + 1280 + g * 128 + kc * 32 + fq * 8);
; #pragma unroll
;     for (int st = 0; st < 8; ++st) {
;       if (st <= LT) {
;         bf16x8 bfm = *(const bf16x8*)(xc + (size_t)(tok0 + st * 16 + fr) * 1536 + 1024 + g * 128 + kc * 32 + fq * 8);
;         G[st] = mfma16(bfm, cf, G[st]);
;       }
;     }
;   }
.LBB0_1685:
	v_mov_b64_e32 v[2:3], s[90:91]
	v_mad_i64_i32 v[2:3], s[10:11], v53, s29, v[2:3]
	s_lshl_b32 s80, s19, 1
	v_lshl_add_u64 v[2:3], v[2:3], 0, s[80:81]
	v_mov_b32_e32 v65, v1
	v_lshl_add_u64 v[2:3], v[2:3], 0, v[64:65]
	s_waitcnt vmcnt(0)
	v_mfma_f32_16x16x32_bf16 v[32:35], v[212:215], v[36:39], v[32:35]
